# cache policy: nt hint also removed from the rowops' bf16 o-row loads (data just written by the preceding GEMM)
# speedup vs baseline: 1.0114x; 1.0024x over previous
.LBB0_28:
	s_movk_i32 s0, 0x4000
	v_cmp_gt_i32_e32 vcc, s0, v104
	s_or_b64 s[0:1], s[6:7], vcc
	s_and_saveexec_b64 s[8:9], s[0:1]
	s_cbranch_execz .LBB0_27
	s_movk_i32 s0, 0x4000
	v_cmp_gt_i32_e32 vcc, s0, v104
	v_min_i32_e32 v0, 0x4000, v104
	v_ashrrev_i32_e32 v1, 31, v104
	v_readlane_b32 s0, v253, 42
	v_ashrrev_i32_e32 v172, 13, v0
	v_add_u32_e32 v0, 0xffffc000, v104
	v_cndmask_b32_e32 v105, 0, v1, vcc
	v_mov_b32_e32 v2, s0
	v_mov_b32_e32 v3, s89
	v_readlane_b32 s0, v255, 17
	v_cndmask_b32_e32 v0, v0, v104, vcc
	v_mov_b32_e32 v1, v105
	v_cndmask_b32_e32 v3, v2, v3, vcc
	v_mov_b32_e32 v2, s0
	v_mov_b32_e32 v4, s88
	v_cndmask_b32_e32 v2, v2, v4, vcc
	v_lshlrev_b64 v[0:1], 12, v[0:1]
	v_lshl_add_u64 v[120:121], v[2:3], 0, v[0:1]
	v_add_u32_e32 v0, s10, v172
	v_mul_hi_i32_i24_e32 v33, 0x6000, v0
	v_mul_i32_i24_e32 v32, 0x6000, v0
	v_lshl_add_u64 v[0:1], v[120:121], 0, v[192:193]
	s_movk_i32 s12, 0x1000
	v_add_co_u32_e32 v2, vcc, s12, v0
	s_movk_i32 s13, 0x2000
	s_nop 0
	v_addc_co_u32_e32 v3, vcc, 0, v1, vcc
	v_add_co_u32_e32 v4, vcc, s13, v0
	global_load_dwordx4 v[92:95], v[0:1], off nt
	global_load_dwordx4 v[88:91], v[0:1], off offset:1024 nt
	global_load_dwordx4 v[84:87], v[0:1], off offset:2048 nt
	global_load_dwordx4 v[80:83], v[0:1], off offset:3072 nt
	v_addc_co_u32_e32 v5, vcc, 0, v1, vcc
	v_add_co_u32_e32 v0, vcc, s73, v0
	global_load_dwordx4 v[76:79], v[4:5], off offset:-4096 nt
	global_load_dwordx4 v[72:75], v[2:3], off offset:1024 nt
	global_load_dwordx4 v[68:71], v[2:3], off offset:2048 nt
	global_load_dwordx4 v[64:67], v[2:3], off offset:3072 nt
	global_load_dwordx4 v[28:31], v[4:5], off nt
	global_load_dwordx4 v[24:27], v[4:5], off offset:1024 nt
	global_load_dwordx4 v[20:23], v[4:5], off offset:2048 nt
	global_load_dwordx4 v[16:19], v[4:5], off offset:3072 nt
	v_addc_co_u32_e32 v1, vcc, 0, v1, vcc
	global_load_dwordx4 v[12:15], v[0:1], off nt
	global_load_dwordx4 v[8:11], v[0:1], off offset:1024 nt
	global_load_dwordx4 v[4:7], v[0:1], off offset:2048 nt
	s_nop 0
	global_load_dwordx4 v[0:3], v[0:1], off offset:3072 nt
	v_add_u32_e32 v34, 1, v104
	v_ashrrev_i32_e32 v35, 31, v34
	v_lshlrev_b64 v[116:117], 11, v[34:35]
	v_add_u32_e32 v34, 2, v104
	v_ashrrev_i32_e32 v35, 31, v34
	v_lshlrev_b64 v[114:115], 11, v[34:35]
	v_add_u32_e32 v34, 3, v104
	v_ashrrev_i32_e32 v35, 31, v34
	v_cmp_lt_i32_e32 vcc, v211, v210
	v_lshlrev_b64 v[112:113], 11, v[34:35]
	v_lshl_add_u64 v[32:33], s[90:91], 0, v[32:33]
	v_cndmask_b32_e32 v34, v209, v211, vcc
	v_cmp_lt_i32_e32 vcc, v212, v210
	v_lshlrev_b32_e32 v107, 2, v34
	v_lshl_add_u64 v[36:37], v[32:33], 0, v[192:193]
	v_cndmask_b32_e32 v34, v209, v212, vcc
	v_cmp_lt_i32_e32 vcc, v206, v210
	v_lshlrev_b32_e32 v109, 2, v34
	s_mov_b64 s[0:1], 0x345d000
	v_cndmask_b32_e32 v34, v209, v206, vcc
	v_cmp_lt_i32_e32 vcc, v213, v210
	v_lshlrev_b32_e32 v111, 2, v34
	v_lshl_add_u64 v[62:63], v[36:37], 0, s[0:1]
	v_cndmask_b32_e32 v34, v209, v213, vcc
	v_cmp_lt_i32_e32 vcc, v216, v210
	v_lshlrev_b32_e32 v169, 2, v34
	s_mov_b32 s0, 0x345d000
	v_cndmask_b32_e32 v34, v209, v216, vcc
	v_cmp_lt_i32_e32 vcc, v217, v210
	v_lshlrev_b32_e32 v170, 2, v34
	v_lshlrev_b64 v[118:119], 11, v[104:105]
	v_cndmask_b32_e32 v34, v209, v217, vcc
	v_add_co_u32_e32 v36, vcc, s0, v36
	v_lshl_add_u64 v[60:61], v[96:97], 0, v[118:119]
	s_nop 0
	v_addc_co_u32_e32 v37, vcc, 0, v37, vcc
	v_lshlrev_b32_e32 v171, 2, v34
	global_load_dwordx4 v[32:35], v[98:99], off
	v_lshl_add_u64 v[140:141], v[96:97], 0, v[116:117]
	global_load_dwordx4 v[36:39], v[36:37], off
	s_nop 0
	global_load_dwordx4 v[40:43], v[98:99], off offset:1024
	global_load_dwordx4 v[44:47], v[62:63], off offset:1024
	global_load_dwordx4 v[48:51], v[98:99], off offset:2048
	global_load_dwordx4 v[52:55], v[62:63], off offset:2048
	s_mov_b32 s0, 0x358637bd
	s_mov_b32 s16, 0x3a800000
	s_mov_b32 s14, 0x800000
	v_lshl_add_u64 v[134:135], v[96:97], 0, v[114:115]
	v_lshl_add_u64 v[124:125], v[96:97], 0, v[112:113]
	s_waitcnt vmcnt(21)
	v_mov_b32_e32 v138, v92
	s_waitcnt vmcnt(17)
	v_mov_b32_e32 v136, v76
	s_waitcnt vmcnt(16)
	v_mov_b32_e32 v142, v72
	v_mov_b32_e32 v143, v74
	v_mov_b32_e32 v74, v73
	v_mov_b32_e32 v137, v78
	s_waitcnt vmcnt(12)
	v_mov_b32_e32 v72, v24
	v_mov_b32_e32 v73, v26
	v_mov_b32_e32 v26, v25
	v_mov_b32_e32 v24, v68
	v_mov_b32_e32 v25, v70
	v_mov_b32_e32 v70, v69
	s_waitcnt vmcnt(7)
	v_mov_b32_e32 v68, v4
	v_mov_b32_e32 v69, v6
	v_mov_b32_e32 v6, v5
	global_load_dwordx4 v[56:59], v[98:99], off offset:3072
	global_load_dwordx2 v[4:5], v[60:61], off offset:1536
	global_load_dwordx2 v[180:181], v[60:61], off offset:1024
	global_load_dwordx2 v[182:183], v[60:61], off offset:512
	global_load_dwordx2 v[184:185], v[60:61], off
	global_load_dwordx2 v[186:187], v[140:141], off offset:1536
	global_load_dwordx2 v[188:189], v[140:141], off offset:1024
	global_load_dwordx2 v[190:191], v[140:141], off offset:512
	global_load_dwordx2 v[224:225], v[140:141], off
	global_load_dwordx2 v[232:233], v[134:135], off offset:1536
	global_load_dwordx2 v[234:235], v[134:135], off offset:1024
	global_load_dwordx2 v[236:237], v[134:135], off offset:512
	global_load_dwordx2 v[238:239], v[134:135], off
	global_load_dwordx2 v[240:241], v[124:125], off offset:1536
	global_load_dwordx2 v[242:243], v[124:125], off offset:1024
	global_load_dwordx2 v[248:249], v[124:125], off offset:512
	global_load_dwordx2 v[250:251], v[124:125], off
	v_mov_b32_e32 v78, v77
	v_mov_b32_e32 v144, v84
	v_mov_b32_e32 v145, v86
	v_mov_b32_e32 v86, v85
	v_mov_b32_e32 v84, v20
	v_mov_b32_e32 v85, v22
	v_mov_b32_e32 v22, v21
	v_mov_b32_e32 v139, v94
	v_mov_b32_e32 v94, v93
	s_waitcnt vmcnt(22)
	v_mov_b32_e32 v130, v32
	v_mov_b32_e32 v131, v34
	s_waitcnt vmcnt(21)
	v_mov_b32_e32 v122, v36
	s_waitcnt vmcnt(19)
	v_mov_b32_e32 v76, v44
	v_mov_b32_e32 v77, v46
	v_mov_b32_e32 v46, v45
	v_mov_b32_e32 v44, v8
	v_mov_b32_e32 v45, v10
	v_mov_b32_e32 v10, v9
	s_waitcnt vmcnt(17)
	v_mov_b32_e32 v8, v52
	v_mov_b32_e32 v9, v54
	v_mov_b32_e32 v54, v53
	v_mov_b32_e32 v123, v38
	v_mov_b32_e32 v38, v37
	v_mov_b32_e32 v36, v28
	v_mov_b32_e32 v37, v30
	v_mov_b32_e32 v30, v29
	v_mov_b32_e32 v28, v12
	v_mov_b32_e32 v29, v14
	v_mov_b32_e32 v14, v13
	v_mov_b32_e32 v12, v88
	v_mov_b32_e32 v13, v90
	v_mov_b32_e32 v90, v89
	v_mov_b32_e32 v34, v33
	v_mov_b32_e32 v32, v80
	v_mov_b32_e32 v33, v82
	v_mov_b32_e32 v82, v81
	s_waitcnt vmcnt(15)
	v_and_b32_e32 v21, 0xffff0000, v5
	v_and_b32_e32 v20, 0xffff0000, v4
	v_lshlrev_b32_e32 v52, 16, v4
	v_lshlrev_b32_e32 v53, 16, v5
	v_mov_b32_e32 v93, v52
	v_mov_b32_e32 v127, v53
	v_mov_b32_e32 v89, v21
	s_waitcnt vmcnt(14)
	v_mov_b32_e32 v4, v180
	v_mov_b32_e32 v5, v181
	v_and_b32_e32 v146, 0xffff0000, v4
	v_and_b32_e32 v147, 0xffff0000, v5
	v_lshlrev_b32_e32 v148, 16, v4
	v_lshlrev_b32_e32 v149, 16, v5
	v_mov_b32_e32 v4, v146
	v_mov_b32_e32 v5, v20
	v_pk_mul_f32 v[4:5], v[4:5], v[4:5]
	v_mov_b32_e32 v92, v148
	v_mov_b32_e32 v126, v149
	v_pk_fma_f32 v[4:5], v[92:93], v[92:93], v[4:5]
	v_mov_b32_e32 v88, v147
	v_pk_fma_f32 v[4:5], v[126:127], v[126:127], v[4:5]
	s_nop 0
	v_pk_fma_f32 v[88:89], v[88:89], v[88:89], v[4:5]
	s_waitcnt vmcnt(13)
	v_mov_b32_e32 v4, v182
	v_mov_b32_e32 v5, v183
	v_and_b32_e32 v151, 0xffff0000, v5
	v_and_b32_e32 v150, 0xffff0000, v4
	v_lshlrev_b32_e32 v152, 16, v4
	v_lshlrev_b32_e32 v153, 16, v5
	v_mov_b32_e32 v127, v152
	v_mov_b32_e32 v129, v153
	v_mov_b32_e32 v61, v151
	s_waitcnt vmcnt(12)
	v_mov_b32_e32 v4, v184
	v_mov_b32_e32 v5, v185
	v_and_b32_e32 v92, 0xffff0000, v4
	v_and_b32_e32 v93, 0xffff0000, v5
	v_lshlrev_b32_e32 v154, 16, v4
	v_lshlrev_b32_e32 v155, 16, v5
	v_mov_b32_e32 v4, v92
	v_mov_b32_e32 v5, v150
	v_pk_mul_f32 v[4:5], v[4:5], v[4:5]
	v_mov_b32_e32 v126, v154
	v_mov_b32_e32 v128, v155
	v_pk_fma_f32 v[4:5], v[126:127], v[126:127], v[4:5]
	v_mov_b32_e32 v60, v93
	v_pk_fma_f32 v[4:5], v[128:129], v[128:129], v[4:5]
	v_mov_b32_e32 v128, v40
	v_mov_b32_e32 v129, v42
	v_mov_b32_e32 v42, v41
	v_pk_fma_f32 v[156:157], v[60:61], v[60:61], v[4:5]
	global_load_dwordx4 v[60:63], v[62:63], off offset:3072
	v_mov_b32_e32 v126, v48
	v_mov_b32_e32 v127, v50
	v_mov_b32_e32 v50, v49
	v_mov_b32_e32 v4, v56
	v_mov_b32_e32 v5, v58
	v_mov_b32_e32 v58, v57
	s_waitcnt vmcnt(12)
	v_mov_b32_e32 v40, v186
	v_mov_b32_e32 v41, v187
	v_and_b32_e32 v159, 0xffff0000, v41
	v_and_b32_e32 v158, 0xffff0000, v40
	v_lshlrev_b32_e32 v160, 16, v40
	v_lshlrev_b32_e32 v161, 16, v41
	s_waitcnt vmcnt(0)
	v_mov_b32_e32 v132, v60
	v_mov_b32_e32 v133, v62
	v_mov_b32_e32 v62, v61
	v_mov_b32_e32 v61, v160
	v_mov_b32_e32 v81, v161
	v_mov_b32_e32 v57, v159
	s_waitcnt vmcnt(0)
	v_mov_b32_e32 v40, v188
	v_mov_b32_e32 v41, v189
	v_and_b32_e32 v48, 0xffff0000, v40
	v_and_b32_e32 v49, 0xffff0000, v41
	v_lshlrev_b32_e32 v162, 16, v40
	v_lshlrev_b32_e32 v163, 16, v41
	v_mov_b32_e32 v40, v48
	v_mov_b32_e32 v41, v158
	v_pk_mul_f32 v[40:41], v[40:41], v[40:41]
	v_mov_b32_e32 v60, v162
	v_mov_b32_e32 v80, v163
	v_pk_fma_f32 v[40:41], v[60:61], v[60:61], v[40:41]
	v_mov_b32_e32 v56, v49
	v_pk_fma_f32 v[40:41], v[80:81], v[80:81], v[40:41]
	s_nop 0
	v_pk_fma_f32 v[40:41], v[56:57], v[56:57], v[40:41]
	s_waitcnt vmcnt(0)
	v_mov_b32_e32 v56, v190
	v_mov_b32_e32 v57, v191
	v_and_b32_e32 v165, 0xffff0000, v57
	v_and_b32_e32 v164, 0xffff0000, v56
	v_lshlrev_b32_e32 v166, 16, v56
	v_lshlrev_b32_e32 v167, 16, v57
	v_mov_b32_e32 v81, v166
	v_mov_b32_e32 v141, v167
	v_mov_b32_e32 v61, v165
	s_waitcnt vmcnt(0)
	v_mov_b32_e32 v56, v224
	v_mov_b32_e32 v57, v225
	v_and_b32_e32 v174, 0xffff0000, v56
	v_and_b32_e32 v175, 0xffff0000, v57
	v_lshlrev_b32_e32 v176, 16, v56
	v_lshlrev_b32_e32 v177, 16, v57
	v_mov_b32_e32 v56, v174
	v_mov_b32_e32 v57, v164
	v_pk_mul_f32 v[56:57], v[56:57], v[56:57]
	v_mov_b32_e32 v80, v176
	v_mov_b32_e32 v140, v177
	v_pk_fma_f32 v[56:57], v[80:81], v[80:81], v[56:57]
	v_mov_b32_e32 v60, v175
	v_pk_fma_f32 v[56:57], v[140:141], v[140:141], v[56:57]
	v_mov_b64_e32 v[140:141], s[0:1]
	v_pk_fma_f32 v[56:57], v[60:61], v[60:61], v[56:57]
	v_mov_b32_e32 v61, v156
	v_mov_b32_e32 v60, v56
	v_mov_b32_e32 v156, v57
	v_pk_add_f32 v[56:57], v[60:61], v[156:157]
	v_mov_b32_e32 v60, v40
	v_mov_b32_e32 v61, v88
	v_pk_add_f32 v[56:57], v[56:57], v[60:61]
	v_mov_b32_e32 v88, v41
	v_pk_add_f32 v[40:41], v[56:57], v[88:89]
	s_nop 0
	s_nop 1
	v_add_f32_dpp v41, v41, v41 quad_perm:[1,0,3,2] row_mask:0xf bank_mask:0xf
	v_add_f32_dpp v40, v40, v40 quad_perm:[1,0,3,2] row_mask:0xf bank_mask:0xf
	s_nop 0
	v_add_f32_dpp v41, v41, v41 quad_perm:[2,3,0,1] row_mask:0xf bank_mask:0xf
	v_add_f32_dpp v40, v40, v40 quad_perm:[2,3,0,1] row_mask:0xf bank_mask:0xf
	s_nop 0
	v_add_f32_dpp v41, v41, v41 row_half_mirror row_mask:0xf bank_mask:0xf
	v_add_f32_dpp v40, v40, v40 row_half_mirror row_mask:0xf bank_mask:0xf
	s_nop 0
	v_add_f32_dpp v41, v41, v41 row_mirror row_mask:0xf bank_mask:0xf
	v_add_f32_dpp v40, v40, v40 row_mirror row_mask:0xf bank_mask:0xf
	s_nop 0
	v_mov_b32_e32 v57, v41
	v_mov_b32_e32 v56, v40
	s_nop 0
	v_permlane16_swap_b32_e32 v41, v57
	v_permlane16_swap_b32_e32 v40, v56
	s_nop 0
	v_add_f32_e32 v41, v41, v57
	v_add_f32_e32 v40, v40, v56
	s_nop 0
	v_mov_b32_e32 v57, v41
	v_mov_b32_e32 v56, v40
	s_nop 0
	v_permlane32_swap_b32_e32 v41, v57
	v_permlane32_swap_b32_e32 v40, v56
	s_nop 0
	v_add_f32_e32 v41, v41, v57
	v_add_f32_e32 v40, v40, v56
	s_nop 0
	s_nop 0
	v_pk_fma_f32 v[156:157], v[40:41], s[16:17], v[140:141] op_sel_hi:[1,0,0]
	s_nop 0
	v_mul_f32_e32 v40, 0x4b800000, v157
	v_cmp_gt_f32_e64 s[0:1], s14, v157
	v_cmp_gt_f32_e32 vcc, s14, v156
	s_nop 0
	v_cndmask_b32_e64 v40, v157, v40, s[0:1]
	v_rsq_f32_e32 v40, v40
	s_nop 0
	v_mul_f32_e32 v41, 0x45800000, v40
	v_cndmask_b32_e64 v178, v40, v41, s[0:1]
	v_pk_mul_f32 v[40:41], v[178:179], v[154:155] op_sel_hi:[0,1]
	v_pk_mul_f32 v[40:41], v[40:41], v[130:131]
	v_pk_mul_f32 v[56:57], v[178:179], v[92:93] op_sel_hi:[0,1]
	v_pk_fma_f32 v[92:93], v[40:41], v[122:123], v[138:139]
	v_pk_mul_f32 v[40:41], v[178:179], v[152:153] op_sel_hi:[0,1]
	v_pk_mul_f32 v[56:57], v[56:57], v[34:35]
	v_pk_mul_f32 v[40:41], v[40:41], v[128:129]
	v_pk_fma_f32 v[88:89], v[56:57], v[38:39], v[94:95]
	v_pk_mul_f32 v[56:57], v[178:179], v[150:151] op_sel_hi:[0,1]
	v_pk_fma_f32 v[80:81], v[40:41], v[76:77], v[12:13]
	v_pk_mul_f32 v[12:13], v[178:179], v[148:149] op_sel_hi:[0,1]
	v_pk_mul_f32 v[56:57], v[56:57], v[42:43]
	v_pk_mul_f32 v[12:13], v[12:13], v[126:127]
	v_pk_fma_f32 v[60:61], v[56:57], v[46:47], v[90:91]
	v_pk_fma_f32 v[56:57], v[12:13], v[8:9], v[144:145]
	v_pk_mul_f32 v[12:13], v[178:179], v[52:53] op_sel_hi:[0,1]
	v_pk_mul_f32 v[20:21], v[178:179], v[20:21] op_sel_hi:[0,1]
	v_pk_mul_f32 v[12:13], v[12:13], v[4:5]
	v_pk_mul_f32 v[20:21], v[20:21], v[58:59]
	v_pk_fma_f32 v[32:33], v[12:13], v[132:133], v[32:33]
	v_pk_fma_f32 v[12:13], v[20:21], v[62:63], v[82:83]
	v_mul_f32_e32 v20, 0x4b800000, v156
	v_cndmask_b32_e32 v20, v156, v20, vcc
	v_rsq_f32_e32 v20, v20
	v_pk_mul_f32 v[40:41], v[178:179], v[146:147] op_sel_hi:[0,1]
	v_pk_mul_f32 v[40:41], v[40:41], v[50:51]
	v_mul_f32_e32 v21, 0x45800000, v20
	v_cndmask_b32_e32 v20, v20, v21, vcc
	v_pk_mul_f32 v[48:49], v[20:21], v[48:49] op_sel_hi:[0,1]
	v_pk_mul_f32 v[48:49], v[48:49], v[50:51]
	v_pk_mul_f32 v[82:83], v[20:21], v[174:175] op_sel_hi:[0,1]
	v_pk_fma_f32 v[48:49], v[48:49], v[54:55], v[70:71]
	v_mov_b32_e32 v70, v64
	v_mov_b32_e32 v71, v66
	v_mov_b32_e32 v66, v65
	v_pk_mul_f32 v[82:83], v[82:83], v[34:35]
	v_pk_mul_f32 v[52:53], v[20:21], v[176:177] op_sel_hi:[0,1]
	v_pk_fma_f32 v[82:83], v[82:83], v[38:39], v[78:79]
	v_pk_mul_f32 v[78:79], v[20:21], v[164:165] op_sel_hi:[0,1]
	v_pk_mul_f32 v[90:91], v[78:79], v[42:43]
	v_pk_mul_f32 v[52:53], v[52:53], v[130:131]
	v_pk_fma_f32 v[74:75], v[90:91], v[46:47], v[74:75]
	v_pk_fma_f32 v[40:41], v[40:41], v[54:55], v[86:87]
	v_pk_fma_f32 v[86:87], v[52:53], v[122:123], v[136:137]
	v_pk_mul_f32 v[52:53], v[20:21], v[166:167] op_sel_hi:[0,1]
	v_pk_mul_f32 v[52:53], v[52:53], v[128:129]
	s_waitcnt vmcnt(0)
	v_mov_b32_e32 v64, v232
	v_mov_b32_e32 v65, v233
	v_and_b32_e32 v91, 0xffff0000, v65
	v_and_b32_e32 v90, 0xffff0000, v64
	v_lshlrev_b32_e32 v94, 16, v64
	v_lshlrev_b32_e32 v95, 16, v65
	v_pk_fma_f32 v[78:79], v[52:53], v[76:77], v[142:143]
	v_pk_mul_f32 v[52:53], v[20:21], v[162:163] op_sel_hi:[0,1]
	v_pk_mul_f32 v[52:53], v[52:53], v[126:127]
	v_mov_b32_e32 v143, v95
	v_pk_fma_f32 v[52:53], v[52:53], v[8:9], v[24:25]
	v_pk_mul_f32 v[24:25], v[20:21], v[160:161] op_sel_hi:[0,1]
	v_pk_mul_f32 v[24:25], v[24:25], v[4:5]
	v_pk_mul_f32 v[20:21], v[20:21], v[158:159] op_sel_hi:[0,1]
	v_pk_fma_f32 v[24:25], v[24:25], v[132:133], v[70:71]
	v_mov_b32_e32 v71, v94
	v_pk_mul_f32 v[20:21], v[20:21], v[58:59]
	s_waitcnt vmcnt(0)
	v_mov_b32_e32 v64, v234
	v_mov_b32_e32 v65, v235
	v_and_b32_e32 v136, 0xffff0000, v64
	v_and_b32_e32 v137, 0xffff0000, v65
	v_lshlrev_b32_e32 v138, 16, v64
	v_lshlrev_b32_e32 v139, 16, v65
	v_mov_b32_e32 v64, v136
	v_mov_b32_e32 v65, v90
	v_pk_mul_f32 v[64:65], v[64:65], v[64:65]
	v_mov_b32_e32 v70, v138
	v_pk_fma_f32 v[64:65], v[70:71], v[70:71], v[64:65]
	v_mov_b32_e32 v142, v139
	v_pk_fma_f32 v[20:21], v[20:21], v[62:63], v[66:67]
	v_mov_b32_e32 v66, v137
	v_mov_b32_e32 v67, v91
	v_pk_fma_f32 v[64:65], v[142:143], v[142:143], v[64:65]
	s_waitcnt vmcnt(0)
	v_mov_b32_e32 v70, v236
	v_mov_b32_e32 v71, v237
	v_lshlrev_b32_e32 v142, 16, v70
	v_pk_fma_f32 v[66:67], v[66:67], v[66:67], v[64:65]
	v_and_b32_e32 v64, 0xffff0000, v70
	s_waitcnt vmcnt(0)
	v_mov_b32_e32 v134, v238
	v_mov_b32_e32 v135, v239
	v_and_b32_e32 v70, 0xffff0000, v134
	v_and_b32_e32 v65, 0xffff0000, v71
	v_lshlrev_b32_e32 v143, 16, v71
	v_and_b32_e32 v71, 0xffff0000, v135
	v_lshlrev_b32_e32 v144, 16, v134
	v_lshlrev_b32_e32 v145, 16, v135
	v_mov_b32_e32 v134, v70
	v_mov_b32_e32 v135, v64
	v_pk_mul_f32 v[134:135], v[134:135], v[134:135]
	v_mov_b32_e32 v148, v144
	v_mov_b32_e32 v149, v142
	v_mov_b32_e32 v150, v145
	v_mov_b32_e32 v151, v143
	v_pk_fma_f32 v[134:135], v[148:149], v[148:149], v[134:135]
	v_mov_b32_e32 v146, v71
	v_mov_b32_e32 v147, v65
	v_pk_fma_f32 v[134:135], v[150:151], v[150:151], v[134:135]
	s_nop 0
	v_pk_fma_f32 v[154:155], v[146:147], v[146:147], v[134:135]
	v_mov_b32_e32 v134, v16
	v_mov_b32_e32 v135, v18
	v_mov_b32_e32 v18, v17
	s_waitcnt vmcnt(0)
	v_mov_b32_e32 v16, v240
	v_mov_b32_e32 v17, v241
	v_and_b32_e32 v147, 0xffff0000, v17
	v_and_b32_e32 v146, 0xffff0000, v16
	v_lshlrev_b32_e32 v148, 16, v16
	v_lshlrev_b32_e32 v149, 16, v17
	v_mov_b32_e32 v159, v148
	v_mov_b32_e32 v161, v149
	v_mov_b32_e32 v157, v147
	s_waitcnt vmcnt(0)
	v_mov_b32_e32 v16, v242
	v_mov_b32_e32 v17, v243
	v_and_b32_e32 v150, 0xffff0000, v16
	v_and_b32_e32 v151, 0xffff0000, v17
	v_lshlrev_b32_e32 v152, 16, v16
	v_lshlrev_b32_e32 v153, 16, v17
	v_mov_b32_e32 v16, v150
	v_mov_b32_e32 v17, v146
	v_pk_mul_f32 v[16:17], v[16:17], v[16:17]
	v_mov_b32_e32 v158, v152
	v_pk_fma_f32 v[16:17], v[158:159], v[158:159], v[16:17]
	v_mov_b32_e32 v160, v153
	v_mov_b32_e32 v156, v151
	v_pk_fma_f32 v[16:17], v[160:161], v[160:161], v[16:17]
	s_waitcnt vmcnt(0)
	v_mov_b32_e32 v158, v248
	v_mov_b32_e32 v159, v249
	v_mov_b32_e32 v124, v250
	v_mov_b32_e32 v125, v251
	v_and_b32_e32 v160, 0xffff0000, v124
	v_pk_fma_f32 v[16:17], v[156:157], v[156:157], v[16:17]
	v_and_b32_e32 v156, 0xffff0000, v158
	v_lshlrev_b32_e32 v158, 16, v158
	v_lshlrev_b32_e32 v124, 16, v124
	v_mov_b32_e32 v162, v160
	v_mov_b32_e32 v163, v156
	v_and_b32_e32 v157, 0xffff0000, v159
	v_lshlrev_b32_e32 v159, 16, v159
	v_and_b32_e32 v161, 0xffff0000, v125
	v_lshlrev_b32_e32 v125, 16, v125
	v_pk_mul_f32 v[162:163], v[162:163], v[162:163]
	v_mov_b32_e32 v166, v124
	v_mov_b32_e32 v167, v158
	v_mov_b32_e32 v174, v125
	v_mov_b32_e32 v175, v159
	v_pk_fma_f32 v[162:163], v[166:167], v[166:167], v[162:163]
	v_mov_b32_e32 v164, v161
	v_mov_b32_e32 v165, v157
	v_pk_fma_f32 v[162:163], v[174:175], v[174:175], v[162:163]
	s_nop 0
	v_pk_fma_f32 v[162:163], v[164:165], v[164:165], v[162:163]
	v_mov_b32_e32 v165, v154
	v_mov_b32_e32 v164, v162
	v_mov_b32_e32 v154, v163
	v_pk_add_f32 v[154:155], v[164:165], v[154:155]
	v_mov_b32_e32 v162, v16
	v_mov_b32_e32 v163, v66
	v_pk_add_f32 v[154:155], v[154:155], v[162:163]
	v_mov_b32_e32 v66, v17
	v_pk_add_f32 v[16:17], v[154:155], v[66:67]
	s_nop 0
	s_nop 1
	v_add_f32_dpp v17, v17, v17 quad_perm:[1,0,3,2] row_mask:0xf bank_mask:0xf
	v_add_f32_dpp v16, v16, v16 quad_perm:[1,0,3,2] row_mask:0xf bank_mask:0xf
	s_nop 0
	v_add_f32_dpp v17, v17, v17 quad_perm:[2,3,0,1] row_mask:0xf bank_mask:0xf
	v_add_f32_dpp v16, v16, v16 quad_perm:[2,3,0,1] row_mask:0xf bank_mask:0xf
	s_nop 0
	v_add_f32_dpp v17, v17, v17 row_half_mirror row_mask:0xf bank_mask:0xf
	v_add_f32_dpp v16, v16, v16 row_half_mirror row_mask:0xf bank_mask:0xf
	s_nop 0
	v_add_f32_dpp v17, v17, v17 row_mirror row_mask:0xf bank_mask:0xf
	v_add_f32_dpp v16, v16, v16 row_mirror row_mask:0xf bank_mask:0xf
	s_nop 0
	v_mov_b32_e32 v67, v17
	v_mov_b32_e32 v66, v16
	s_nop 0
	v_permlane16_swap_b32_e32 v17, v67
	v_permlane16_swap_b32_e32 v16, v66
	s_nop 0
	v_add_f32_e32 v17, v17, v67
	v_add_f32_e32 v16, v16, v66
	s_nop 0
	v_mov_b32_e32 v67, v17
	v_mov_b32_e32 v66, v16
	s_nop 0
	v_permlane32_swap_b32_e32 v17, v67
	v_permlane32_swap_b32_e32 v16, v66
	s_nop 0
	v_add_f32_e32 v17, v17, v67
	v_add_f32_e32 v16, v16, v66
	s_nop 0
	s_nop 0
	v_pk_fma_f32 v[140:141], v[16:17], s[16:17], v[140:141] op_sel_hi:[1,0,0]
	s_nop 0
	v_mul_f32_e32 v16, 0x4b800000, v141
	v_cmp_gt_f32_e64 s[0:1], s14, v141
	v_cmp_gt_f32_e32 vcc, s14, v140
	s_nop 0
	v_cndmask_b32_e64 v16, v141, v16, s[0:1]
	v_rsq_f32_e32 v16, v16
	s_nop 0
	v_mul_f32_e32 v17, 0x45800000, v16
	v_cndmask_b32_e64 v16, v16, v17, s[0:1]
	v_pk_mul_f32 v[66:67], v[16:17], v[144:145] op_sel_hi:[0,1]
	v_pk_mul_f32 v[70:71], v[16:17], v[70:71] op_sel_hi:[0,1]
	v_pk_mul_f32 v[66:67], v[130:131], v[66:67]
	v_pk_mul_f32 v[144:145], v[34:35], v[70:71]
	v_pk_fma_f32 v[70:71], v[122:123], v[66:67], v[36:37]
	v_pk_fma_f32 v[66:67], v[144:145], v[38:39], v[30:31]
	v_pk_mul_f32 v[30:31], v[16:17], v[142:143] op_sel_hi:[0,1]
	v_pk_mul_f32 v[36:37], v[16:17], v[64:65] op_sel_hi:[0,1]
	v_pk_mul_f32 v[30:31], v[30:31], v[128:129]
	v_pk_mul_f32 v[36:37], v[36:37], v[42:43]
	v_pk_fma_f32 v[64:65], v[30:31], v[76:77], v[72:73]
	v_pk_fma_f32 v[36:37], v[36:37], v[46:47], v[26:27]
	v_pk_mul_f32 v[26:27], v[16:17], v[138:139] op_sel_hi:[0,1]
	v_pk_mul_f32 v[30:31], v[16:17], v[136:137] op_sel_hi:[0,1]
	v_pk_mul_f32 v[26:27], v[26:27], v[126:127]
	v_pk_mul_f32 v[72:73], v[30:31], v[50:51]
	v_pk_fma_f32 v[30:31], v[26:27], v[8:9], v[84:85]
	v_pk_fma_f32 v[26:27], v[72:73], v[54:55], v[22:23]
	v_pk_mul_f32 v[22:23], v[16:17], v[94:95] op_sel_hi:[0,1]
	v_pk_mul_f32 v[16:17], v[16:17], v[90:91] op_sel_hi:[0,1]
	v_pk_mul_f32 v[16:17], v[16:17], v[58:59]
	v_pk_mul_f32 v[22:23], v[22:23], v[4:5]
	v_pk_fma_f32 v[16:17], v[16:17], v[62:63], v[18:19]
	v_mul_f32_e32 v18, 0x4b800000, v140
	v_cndmask_b32_e32 v18, v140, v18, vcc
	v_rsq_f32_e32 v18, v18
	v_pk_fma_f32 v[22:23], v[22:23], v[132:133], v[134:135]
	v_mul_f32_e32 v19, 0x45800000, v18
	v_cndmask_b32_e32 v18, v18, v19, vcc
	v_pk_mul_f32 v[72:73], v[18:19], v[124:125] op_sel_hi:[0,1]
	v_pk_mul_f32 v[84:85], v[18:19], v[160:161] op_sel_hi:[0,1]
	v_pk_mul_f32 v[72:73], v[130:131], v[72:73]
	v_pk_mul_f32 v[34:35], v[34:35], v[84:85]
	v_pk_fma_f32 v[84:85], v[122:123], v[72:73], v[28:29]
	v_pk_fma_f32 v[72:73], v[38:39], v[34:35], v[14:15]
	v_pk_mul_f32 v[14:15], v[18:19], v[158:159] op_sel_hi:[0,1]
	v_pk_mul_f32 v[28:29], v[18:19], v[156:157] op_sel_hi:[0,1]
	v_pk_mul_f32 v[14:15], v[128:129], v[14:15]
	v_pk_mul_f32 v[28:29], v[42:43], v[28:29]
	v_pk_fma_f32 v[42:43], v[14:15], v[76:77], v[44:45]
	v_pk_fma_f32 v[38:39], v[28:29], v[46:47], v[10:11]
	v_pk_mul_f32 v[10:11], v[18:19], v[152:153] op_sel_hi:[0,1]
	v_pk_mul_f32 v[14:15], v[18:19], v[150:151] op_sel_hi:[0,1]
	v_pk_mul_f32 v[10:11], v[10:11], v[126:127]
	v_pk_mul_f32 v[14:15], v[14:15], v[50:51]
	v_pk_fma_f32 v[34:35], v[10:11], v[8:9], v[68:69]
	v_pk_fma_f32 v[28:29], v[14:15], v[54:55], v[6:7]
	v_pk_mul_f32 v[6:7], v[18:19], v[148:149] op_sel_hi:[0,1]
	v_mov_b32_e32 v8, v0
	v_mov_b32_e32 v9, v2
	v_mov_b32_e32 v2, v1
	v_lshlrev_b64 v[0:1], 12, v[104:105]
	v_pk_mul_f32 v[4:5], v[6:7], v[4:5]
	v_pk_mul_f32 v[6:7], v[18:19], v[146:147] op_sel_hi:[0,1]
	v_lshl_add_u64 v[0:1], s[88:89], 0, v[0:1]
	v_pk_mul_f32 v[6:7], v[6:7], v[58:59]
	v_cndmask_b32_e64 v1, v121, v1, s[2:3]
	v_cndmask_b32_e64 v0, v120, v0, s[2:3]
	v_pk_fma_f32 v[14:15], v[4:5], v[132:133], v[8:9]
	v_pk_fma_f32 v[18:19], v[6:7], v[62:63], v[2:3]
	v_lshl_add_u64 v[4:5], v[0:1], 0, v[192:193]
	v_mov_b32_e32 v0, v92
	v_mov_b32_e32 v1, v88
	v_mov_b32_e32 v2, v93
	v_mov_b32_e32 v3, v89
	global_store_dwordx4 v[4:5], v[0:3], off nt
	v_add_co_u32_e32 v6, vcc, s12, v4
	s_nop 0
	v_mov_b32_e32 v0, v80
	v_mov_b32_e32 v1, v60
	v_mov_b32_e32 v2, v81
	v_mov_b32_e32 v3, v61
	global_store_dwordx4 v[4:5], v[0:3], off offset:1024 nt
	v_addc_co_u32_e32 v7, vcc, 0, v5, vcc
	s_nop 0
	v_mov_b32_e32 v0, v56
	v_mov_b32_e32 v1, v40
	v_mov_b32_e32 v2, v57
	v_mov_b32_e32 v3, v41
	global_store_dwordx4 v[4:5], v[0:3], off offset:2048 nt
	v_add_co_u32_e32 v8, vcc, s13, v4
	s_nop 0
	v_mov_b32_e32 v0, v32
	v_mov_b32_e32 v1, v12
	v_mov_b32_e32 v2, v33
	v_mov_b32_e32 v3, v13
	global_store_dwordx4 v[4:5], v[0:3], off offset:3072 nt
	v_addc_co_u32_e32 v9, vcc, 0, v5, vcc
	s_nop 0
	v_mov_b32_e32 v0, v86
	v_mov_b32_e32 v1, v82
	v_mov_b32_e32 v2, v87
	v_mov_b32_e32 v3, v83
	global_store_dwordx4 v[8:9], v[0:3], off offset:-4096 nt
	v_add_co_u32_e32 v4, vcc, s73, v4
	s_nop 0
	v_mov_b32_e32 v0, v78
	v_mov_b32_e32 v1, v74
	v_mov_b32_e32 v2, v79
	v_mov_b32_e32 v3, v75
	global_store_dwordx4 v[6:7], v[0:3], off offset:1024 nt
	v_addc_co_u32_e32 v5, vcc, 0, v5, vcc
	s_nop 0
	v_mov_b32_e32 v0, v52
	v_mov_b32_e32 v1, v48
	v_mov_b32_e32 v2, v53
	v_mov_b32_e32 v3, v49
	global_store_dwordx4 v[6:7], v[0:3], off offset:2048 nt
	s_andn2_b64 vcc, exec, s[4:5]
	s_nop 0
	v_mov_b32_e32 v0, v24
	v_mov_b32_e32 v1, v20
	v_mov_b32_e32 v2, v25
	v_mov_b32_e32 v3, v21
	global_store_dwordx4 v[6:7], v[0:3], off offset:3072 nt
	s_nop 1
	v_mov_b32_e32 v0, v70
	v_mov_b32_e32 v1, v66
	v_mov_b32_e32 v2, v71
	v_mov_b32_e32 v3, v67
	global_store_dwordx4 v[8:9], v[0:3], off nt
	s_nop 1
	v_mov_b32_e32 v0, v64
	v_mov_b32_e32 v1, v36
	v_mov_b32_e32 v2, v65
	v_mov_b32_e32 v3, v37
	global_store_dwordx4 v[8:9], v[0:3], off offset:1024 nt
	s_nop 1
	v_mov_b32_e32 v0, v30
	v_mov_b32_e32 v1, v26
	v_mov_b32_e32 v2, v31
	v_mov_b32_e32 v3, v27
	global_store_dwordx4 v[8:9], v[0:3], off offset:2048 nt
	s_nop 1
	v_mov_b32_e32 v0, v22
	v_mov_b32_e32 v1, v16
	v_mov_b32_e32 v2, v23
	v_mov_b32_e32 v3, v17
	global_store_dwordx4 v[8:9], v[0:3], off offset:3072 nt
	s_nop 1
	v_mov_b32_e32 v0, v84
	v_mov_b32_e32 v1, v72
	v_mov_b32_e32 v2, v85
	v_mov_b32_e32 v3, v73
	global_store_dwordx4 v[4:5], v[0:3], off nt
	s_nop 1
	v_mov_b32_e32 v0, v42
	v_mov_b32_e32 v1, v38
	v_mov_b32_e32 v2, v43
	v_mov_b32_e32 v3, v39
	global_store_dwordx4 v[4:5], v[0:3], off offset:1024 nt
	s_nop 1
	v_mov_b32_e32 v0, v34
	v_mov_b32_e32 v1, v28
	v_mov_b32_e32 v2, v35
	v_mov_b32_e32 v3, v29
	global_store_dwordx4 v[4:5], v[0:3], off offset:2048 nt
	s_nop 1
	v_mov_b32_e32 v0, v14
	v_mov_b32_e32 v1, v18
	v_mov_b32_e32 v2, v15
	v_mov_b32_e32 v3, v19
	global_store_dwordx4 v[4:5], v[0:3], off offset:3072 nt
	s_cbranch_vccnz .LBB0_27
	v_mov_b32_e32 v4, v88
	v_mov_b32_e32 v5, v60
	v_mov_b32_e32 v2, v92
	v_mov_b32_e32 v3, v80
	v_pk_mul_f32 v[4:5], v[4:5], v[4:5]
	v_mov_b32_e32 v6, v40
	v_pk_fma_f32 v[2:3], v[2:3], v[2:3], v[4:5]
	v_mov_b32_e32 v4, v93
	v_mov_b32_e32 v5, v81
	v_pk_fma_f32 v[2:3], v[4:5], v[4:5], v[2:3]
	v_mov_b32_e32 v4, v89
	v_mov_b32_e32 v5, v61
	v_mov_b32_e32 v7, v12
	v_pk_fma_f32 v[2:3], v[4:5], v[4:5], v[2:3]
	v_mov_b32_e32 v4, v56
	v_mov_b32_e32 v5, v32
	v_pk_mul_f32 v[6:7], v[6:7], v[6:7]
	v_mov_b32_e32 v8, v82
	v_pk_fma_f32 v[4:5], v[4:5], v[4:5], v[6:7]
	v_mov_b32_e32 v6, v57
	v_mov_b32_e32 v7, v33
	v_pk_fma_f32 v[4:5], v[6:7], v[6:7], v[4:5]
	v_mov_b32_e32 v6, v41
	v_mov_b32_e32 v7, v13
	v_mov_b32_e32 v9, v74
	v_pk_fma_f32 v[4:5], v[6:7], v[6:7], v[4:5]
	v_mov_b32_e32 v6, v86
	v_mov_b32_e32 v7, v78
	v_pk_mul_f32 v[8:9], v[8:9], v[8:9]
	v_mov_b32_e32 v10, v48
	v_pk_fma_f32 v[6:7], v[6:7], v[6:7], v[8:9]
	v_mov_b32_e32 v8, v87
	v_mov_b32_e32 v9, v79
	v_pk_fma_f32 v[6:7], v[8:9], v[8:9], v[6:7]
	v_mov_b32_e32 v8, v83
	v_mov_b32_e32 v9, v75
	v_mov_b32_e32 v11, v20
	v_pk_fma_f32 v[6:7], v[8:9], v[8:9], v[6:7]
	v_mov_b32_e32 v8, v52
	v_mov_b32_e32 v9, v24
	v_pk_mul_f32 v[10:11], v[10:11], v[10:11]
	s_mov_b32 s0, 0x358637bd
	v_pk_fma_f32 v[8:9], v[8:9], v[8:9], v[10:11]
	v_mov_b32_e32 v10, v53
	v_mov_b32_e32 v11, v25
	v_pk_fma_f32 v[8:9], v[10:11], v[10:11], v[8:9]
	v_mov_b32_e32 v10, v49
	v_mov_b32_e32 v11, v21
	v_pk_fma_f32 v[8:9], v[10:11], v[10:11], v[8:9]
	v_mov_b32_e32 v10, v6
	v_mov_b32_e32 v11, v2
	v_mov_b32_e32 v2, v7
	v_pk_add_f32 v[2:3], v[10:11], v[2:3]
	v_mov_b32_e32 v6, v8
	v_mov_b32_e32 v7, v4
	v_pk_add_f32 v[2:3], v[2:3], v[6:7]
	v_mov_b32_e32 v4, v9
	v_pk_add_f32 v[2:3], v[2:3], v[4:5]
	s_mov_b32 s14, 0x3a800000
	s_mov_b32 s12, 0x800000
	v_mov_b32_e32 v7, v36
	v_mov_b32_e32 v8, v26
	v_mov_b32_e32 v9, v16
	v_pk_mul_f32 v[8:9], v[8:9], v[8:9]
	v_mov_b32_e32 v10, v72
	v_mov_b32_e32 v11, v38
	v_pk_mul_f32 v[10:11], v[10:11], v[10:11]
	v_mov_b32_e32 v50, v28
	v_mov_b32_e32 v51, v18
	v_pk_mul_f32 v[50:51], v[50:51], v[50:51]
	v_add_u32_e32 v0, v172, v168
	v_mul_hi_i32_i24_e32 v1, 0x6000, v0
	v_mul_i32_i24_e32 v0, 0x6000, v0
	v_lshl_add_u64 v[0:1], s[96:97], 0, v[0:1]
	v_lshl_add_u64 v[62:63], v[0:1], 0, v[192:193]
	v_lshl_add_u64 v[58:59], v[102:103], 0, v[118:119]
	s_nop 0
	s_nop 1
	v_add_f32_dpp v3, v3, v3 quad_perm:[1,0,3,2] row_mask:0xf bank_mask:0xf
	v_add_f32_dpp v2, v2, v2 quad_perm:[1,0,3,2] row_mask:0xf bank_mask:0xf
	s_nop 0
	v_add_f32_dpp v3, v3, v3 quad_perm:[2,3,0,1] row_mask:0xf bank_mask:0xf
	v_add_f32_dpp v2, v2, v2 quad_perm:[2,3,0,1] row_mask:0xf bank_mask:0xf
	s_nop 0
	v_add_f32_dpp v3, v3, v3 row_half_mirror row_mask:0xf bank_mask:0xf
	v_add_f32_dpp v2, v2, v2 row_half_mirror row_mask:0xf bank_mask:0xf
	s_nop 0
	v_add_f32_dpp v3, v3, v3 row_mirror row_mask:0xf bank_mask:0xf
	v_add_f32_dpp v2, v2, v2 row_mirror row_mask:0xf bank_mask:0xf
	s_nop 0
	v_mov_b32_e32 v5, v3
	v_mov_b32_e32 v4, v2
	s_nop 0
	v_permlane16_swap_b32_e32 v3, v5
	v_permlane16_swap_b32_e32 v2, v4
	s_nop 0
	v_add_f32_e32 v3, v3, v5
	v_add_f32_e32 v2, v2, v4
	s_nop 0
	v_mov_b32_e32 v5, v3
	v_mov_b32_e32 v4, v2
	s_nop 0
	v_permlane32_swap_b32_e32 v3, v5
	v_permlane32_swap_b32_e32 v2, v4
	s_nop 0
	v_add_f32_e32 v3, v3, v5
	v_add_f32_e32 v2, v2, v4
	s_nop 0
	v_mov_b64_e32 v[4:5], s[0:1]
	v_pk_fma_f32 v[2:3], v[2:3], s[14:15], v[4:5] op_sel_hi:[1,0,0]
	s_nop 0
	v_mul_f32_e32 v6, 0x4b800000, v3
	v_cmp_gt_f32_e64 s[0:1], s12, v3
	v_cmp_gt_f32_e32 vcc, s12, v2
	s_nop 0
	v_cndmask_b32_e64 v3, v3, v6, s[0:1]
	v_rsq_f32_e32 v3, v3
	s_nop 0
	v_mul_f32_e32 v6, 0x45800000, v3
	v_cndmask_b32_e64 v46, v3, v6, s[0:1]
	v_mul_f32_e32 v3, 0x4b800000, v2
	v_cndmask_b32_e32 v2, v2, v3, vcc
	v_rsq_f32_e32 v2, v2
	v_mov_b32_e32 v6, v66
	v_pk_mul_f32 v[6:7], v[6:7], v[6:7]
	v_pk_mul_f32 v[88:89], v[88:89], v[46:47] op_sel_hi:[1,0]
	v_mul_f32_e32 v3, 0x45800000, v2
	v_cndmask_b32_e32 v44, v2, v3, vcc
	v_mov_b32_e32 v2, v70
	v_mov_b32_e32 v3, v64
	v_pk_fma_f32 v[2:3], v[2:3], v[2:3], v[6:7]
	v_mov_b32_e32 v6, v71
	v_mov_b32_e32 v7, v65
	v_pk_fma_f32 v[2:3], v[6:7], v[6:7], v[2:3]
	v_mov_b32_e32 v6, v67
	v_mov_b32_e32 v7, v37
	v_pk_fma_f32 v[2:3], v[6:7], v[6:7], v[2:3]
	v_mov_b32_e32 v6, v30
	v_mov_b32_e32 v7, v22
	v_pk_fma_f32 v[6:7], v[6:7], v[6:7], v[8:9]
	v_mov_b32_e32 v8, v31
	v_mov_b32_e32 v9, v23
	v_pk_fma_f32 v[6:7], v[8:9], v[8:9], v[6:7]
	v_mov_b32_e32 v8, v27
	v_mov_b32_e32 v9, v17
	v_pk_fma_f32 v[6:7], v[8:9], v[8:9], v[6:7]
	v_mov_b32_e32 v8, v84
	v_mov_b32_e32 v9, v42
	v_pk_fma_f32 v[8:9], v[8:9], v[8:9], v[10:11]
	v_mov_b32_e32 v10, v85
	v_mov_b32_e32 v11, v43
	v_pk_fma_f32 v[8:9], v[10:11], v[10:11], v[8:9]
	v_mov_b32_e32 v10, v73
	v_mov_b32_e32 v11, v39
	v_pk_fma_f32 v[8:9], v[10:11], v[10:11], v[8:9]
	v_mov_b32_e32 v10, v34
	v_mov_b32_e32 v11, v14
	v_pk_fma_f32 v[10:11], v[10:11], v[10:11], v[50:51]
	v_mov_b32_e32 v50, v35
	v_mov_b32_e32 v51, v15
	v_pk_fma_f32 v[10:11], v[50:51], v[50:51], v[10:11]
	v_mov_b32_e32 v50, v29
	v_mov_b32_e32 v51, v19
	v_pk_fma_f32 v[10:11], v[50:51], v[50:51], v[10:11]
	v_mov_b32_e32 v50, v8
	v_mov_b32_e32 v51, v2
	v_mov_b32_e32 v2, v9
	v_pk_add_f32 v[2:3], v[50:51], v[2:3]
	v_mov_b32_e32 v8, v10
	v_mov_b32_e32 v9, v6
	v_pk_add_f32 v[2:3], v[2:3], v[8:9]
	v_mov_b32_e32 v6, v11
	v_pk_add_f32 v[2:3], v[2:3], v[6:7]
	v_mov_b32_e32 v107, v193
	v_mov_b32_e32 v109, v193
	v_mov_b32_e32 v111, v193
	s_nop 0
	s_nop 1
	v_add_f32_dpp v3, v3, v3 quad_perm:[1,0,3,2] row_mask:0xf bank_mask:0xf
	v_add_f32_dpp v2, v2, v2 quad_perm:[1,0,3,2] row_mask:0xf bank_mask:0xf
	s_nop 0
	v_add_f32_dpp v3, v3, v3 quad_perm:[2,3,0,1] row_mask:0xf bank_mask:0xf
	v_add_f32_dpp v2, v2, v2 quad_perm:[2,3,0,1] row_mask:0xf bank_mask:0xf
	s_nop 0
	v_add_f32_dpp v3, v3, v3 row_half_mirror row_mask:0xf bank_mask:0xf
	v_add_f32_dpp v2, v2, v2 row_half_mirror row_mask:0xf bank_mask:0xf
	s_nop 0
	v_add_f32_dpp v3, v3, v3 row_mirror row_mask:0xf bank_mask:0xf
	v_add_f32_dpp v2, v2, v2 row_mirror row_mask:0xf bank_mask:0xf
	s_nop 0
	v_mov_b32_e32 v7, v3
	v_mov_b32_e32 v6, v2
	s_nop 0
	v_permlane16_swap_b32_e32 v3, v7
	v_permlane16_swap_b32_e32 v2, v6
	s_nop 0
	v_add_f32_e32 v3, v3, v7
	v_add_f32_e32 v2, v2, v6
	s_nop 0
	v_mov_b32_e32 v7, v3
	v_mov_b32_e32 v6, v2
	s_nop 0
	v_permlane32_swap_b32_e32 v3, v7
	v_permlane32_swap_b32_e32 v2, v6
	s_nop 0
	v_add_f32_e32 v3, v3, v7
	v_add_f32_e32 v2, v2, v6
	s_nop 0
	s_nop 0
	v_pk_fma_f32 v[2:3], v[2:3], s[14:15], v[4:5] op_sel_hi:[1,0,0]
	s_nop 0
	v_mul_f32_e32 v4, 0x4b800000, v3
	v_cmp_gt_f32_e64 s[0:1], s12, v3
	v_cmp_gt_f32_e32 vcc, s12, v2
	s_nop 0
	v_cndmask_b32_e64 v3, v3, v4, s[0:1]
	v_rsq_f32_e32 v3, v3
	s_nop 0
	v_mul_f32_e32 v4, 0x45800000, v3
	v_cndmask_b32_e64 v54, v3, v4, s[0:1]
	v_mul_f32_e32 v3, 0x4b800000, v2
	v_cndmask_b32_e32 v2, v2, v3, vcc
	v_rsq_f32_e32 v2, v2
	s_mov_b64 s[0:1], 0x1000
	v_lshl_add_u64 v[68:69], v[0:1], 0, s[0:1]
	v_lshl_add_u64 v[4:5], v[68:69], 0, v[192:193]
	v_mul_f32_e32 v3, 0x45800000, v2
	v_cndmask_b32_e32 v50, v2, v3, vcc
	global_load_dwordx4 v[0:3], v[100:101], off
	global_load_dwordx4 v[8:11], v[4:5], off
	s_nop 0
	global_load_dwordx4 v[4:7], v[62:63], off
	v_pk_mul_f32 v[66:67], v[66:67], v[54:55] op_sel_hi:[1,0]
	v_pk_mul_f32 v[36:37], v[36:37], v[54:55] op_sel_hi:[1,0]
	v_pk_mul_f32 v[26:27], v[26:27], v[54:55] op_sel_hi:[1,0]
	s_waitcnt vmcnt(2)
	v_mov_b32_e32 v90, v0
	s_waitcnt vmcnt(1)
	v_mov_b32_e32 v76, v8
	v_mov_b32_e32 v77, v10
	v_mov_b32_e32 v10, v9
	v_pk_mul_f32 v[8:9], v[92:93], v[46:47] op_sel_hi:[1,0]
	v_mov_b32_e32 v91, v2
	v_pk_add_f32 v[76:77], v[76:77], 1.0 op_sel_hi:[1,0]
	v_pk_mul_f32 v[8:9], v[8:9], v[90:91]
	s_waitcnt vmcnt(0)
	v_mov_b32_e32 v92, v4
	v_mov_b32_e32 v93, v6
	v_mov_b32_e32 v2, v1
	v_pk_add_f32 v[10:11], v[10:11], 1.0 op_sel_hi:[1,0]
	v_pk_fma_f32 v[8:9], v[8:9], v[76:77], v[92:93]
	v_pk_mul_f32 v[0:1], v[88:89], v[2:3]
	v_mov_b32_e32 v6, v5
	v_pk_fma_f32 v[0:1], v[0:1], v[10:11], v[6:7]
	v_cvt_pk_bf16_f32 v0, v8, v0
	v_cvt_pk_bf16_f32 v1, v9, v1
	v_pk_mul_f32 v[4:5], v[86:87], v[44:45] op_sel_hi:[1,0]
	v_pk_mul_f32 v[8:9], v[82:83], v[44:45] op_sel_hi:[1,0]
	v_pk_mul_f32 v[4:5], v[4:5], v[90:91]
	v_pk_mul_f32 v[8:9], v[8:9], v[2:3]
	v_pk_fma_f32 v[4:5], v[4:5], v[76:77], v[92:93]
	v_pk_fma_f32 v[8:9], v[8:9], v[10:11], v[6:7]
	v_cvt_pk_bf16_f32 v5, v5, v9
	v_cvt_pk_bf16_f32 v4, v4, v8
	v_pk_mul_f32 v[8:9], v[70:71], v[54:55] op_sel_hi:[1,0]
	v_pk_mul_f32 v[66:67], v[2:3], v[66:67]
	v_pk_mul_f32 v[8:9], v[90:91], v[8:9]
	v_pk_fma_f32 v[66:67], v[66:67], v[10:11], v[6:7]
	v_pk_fma_f32 v[8:9], v[8:9], v[76:77], v[92:93]
	v_pk_mul_f32 v[70:71], v[72:73], v[50:51] op_sel_hi:[1,0]
	v_cvt_pk_bf16_f32 v9, v9, v67
	v_and_b32_sdwa v47, v8, v218 dst_sel:DWORD dst_unused:UNUSED_PAD src0_sel:WORD_1 src1_sel:DWORD
	v_add3_u32 v8, v8, v47, s80
	v_and_b32_sdwa v47, v66, v218 dst_sel:DWORD dst_unused:UNUSED_PAD src0_sel:WORD_1 src1_sel:DWORD
	v_add3_u32 v47, v66, v47, s80
	v_pk_mul_f32 v[66:67], v[84:85], v[50:51] op_sel_hi:[1,0]
	v_pk_mul_f32 v[2:3], v[2:3], v[70:71]
	v_pk_mul_f32 v[66:67], v[90:91], v[66:67]
	v_pk_fma_f32 v[2:3], v[10:11], v[2:3], v[6:7]
	v_pk_fma_f32 v[66:67], v[76:77], v[66:67], v[92:93]
	global_store_dwordx2 v[58:59], v[0:1], off
	v_lshl_add_u64 v[0:1], v[102:103], 0, v[116:117]
	v_and_b32_e32 v47, 0xffff0000, v47
	v_cvt_pk_bf16_f32 v3, v67, v3
	v_cvt_pk_bf16_f32 v2, v66, v2
	global_store_dwordx2 v[0:1], v[4:5], off
	v_lshl_add_u64 v[4:5], v[102:103], 0, v[114:115]
	v_or_b32_sdwa v8, v47, v8 dst_sel:DWORD dst_unused:UNUSED_PAD src0_sel:DWORD src1_sel:WORD_1
	global_store_dwordx2 v[4:5], v[8:9], off
	v_lshl_add_u64 v[8:9], v[102:103], 0, v[112:113]
	global_store_dwordx2 v[8:9], v[2:3], off
	v_lshl_add_u64 v[2:3], v[68:69], 0, v[106:107]
	global_load_dwordx4 v[70:73], v[100:101], off offset:1024
	global_load_dwordx4 v[82:85], v[2:3], off
	global_load_dwordx4 v[86:89], v[62:63], off offset:1024
	v_pk_mul_f32 v[10:11], v[80:81], v[46:47] op_sel_hi:[1,0]
	v_pk_mul_f32 v[60:61], v[60:61], v[46:47] op_sel_hi:[1,0]
	s_waitcnt vmcnt(2)
	v_mov_b32_e32 v66, v70
	s_waitcnt vmcnt(1)
	v_mov_b32_e32 v2, v82
	v_mov_b32_e32 v3, v84
	v_mov_b32_e32 v67, v72
	v_pk_add_f32 v[2:3], v[2:3], 1.0 op_sel_hi:[1,0]
	v_mov_b32_e32 v84, v83
	v_pk_mul_f32 v[10:11], v[10:11], v[66:67]
	s_waitcnt vmcnt(0)
	v_mov_b32_e32 v76, v86
	v_mov_b32_e32 v77, v88
	v_mov_b32_e32 v72, v71
	v_pk_add_f32 v[6:7], v[84:85], 1.0 op_sel_hi:[1,0]
	v_pk_fma_f32 v[10:11], v[10:11], v[2:3], v[76:77]
	v_pk_mul_f32 v[60:61], v[60:61], v[72:73]
	v_mov_b32_e32 v88, v87
	v_pk_fma_f32 v[60:61], v[60:61], v[6:7], v[88:89]
	v_and_b32_sdwa v45, v11, v218 dst_sel:DWORD dst_unused:UNUSED_PAD src0_sel:WORD_1 src1_sel:DWORD
	v_cvt_pk_bf16_f32 v10, v10, v60
	v_add3_u32 v11, v11, v45, s80
	v_and_b32_sdwa v45, v61, v218 dst_sel:DWORD dst_unused:UNUSED_PAD src0_sel:WORD_1 src1_sel:DWORD
	v_add3_u32 v45, v61, v45, s80
	v_and_b32_e32 v45, 0xffff0000, v45
	v_or_b32_sdwa v11, v45, v11 dst_sel:DWORD dst_unused:UNUSED_PAD src0_sel:DWORD src1_sel:WORD_1
	global_store_dwordx2 v[58:59], v[10:11], off offset:512
	v_pk_mul_f32 v[10:11], v[78:79], v[44:45] op_sel_hi:[1,0]
	v_pk_mul_f32 v[60:61], v[74:75], v[44:45] op_sel_hi:[1,0]
	v_pk_mul_f32 v[10:11], v[10:11], v[66:67]
	v_pk_mul_f32 v[60:61], v[60:61], v[72:73]
	v_pk_fma_f32 v[10:11], v[10:11], v[2:3], v[76:77]
	v_pk_fma_f32 v[60:61], v[60:61], v[6:7], v[88:89]
	v_cvt_pk_bf16_f32 v11, v11, v61
	v_cvt_pk_bf16_f32 v10, v10, v60
	global_store_dwordx2 v[0:1], v[10:11], off offset:512
	v_pk_mul_f32 v[10:11], v[64:65], v[54:55] op_sel_hi:[1,0]
	v_pk_mul_f32 v[36:37], v[36:37], v[72:73]
	v_pk_mul_f32 v[10:11], v[10:11], v[66:67]
	v_pk_fma_f32 v[36:37], v[36:37], v[6:7], v[88:89]
	v_pk_fma_f32 v[10:11], v[10:11], v[2:3], v[76:77]
	s_nop 0
	v_and_b32_sdwa v45, v11, v218 dst_sel:DWORD dst_unused:UNUSED_PAD src0_sel:WORD_1 src1_sel:DWORD
	v_and_b32_sdwa v47, v10, v218 dst_sel:DWORD dst_unused:UNUSED_PAD src0_sel:WORD_1 src1_sel:DWORD
	v_add3_u32 v10, v10, v47, s80
	v_add3_u32 v11, v11, v45, s80
	v_and_b32_sdwa v45, v37, v218 dst_sel:DWORD dst_unused:UNUSED_PAD src0_sel:WORD_1 src1_sel:DWORD
	v_and_b32_sdwa v47, v36, v218 dst_sel:DWORD dst_unused:UNUSED_PAD src0_sel:WORD_1 src1_sel:DWORD
	v_add3_u32 v37, v37, v45, s80
	v_add3_u32 v36, v36, v47, s80
	v_and_b32_e32 v37, 0xffff0000, v37
	v_and_b32_e32 v36, 0xffff0000, v36
	v_or_b32_sdwa v11, v37, v11 dst_sel:DWORD dst_unused:UNUSED_PAD src0_sel:DWORD src1_sel:WORD_1
	v_or_b32_sdwa v10, v36, v10 dst_sel:DWORD dst_unused:UNUSED_PAD src0_sel:DWORD src1_sel:WORD_1
	global_store_dwordx2 v[4:5], v[10:11], off offset:512
	v_pk_mul_f32 v[10:11], v[42:43], v[50:51] op_sel_hi:[1,0]
	v_pk_mul_f32 v[40:41], v[40:41], v[46:47] op_sel_hi:[1,0]
	v_pk_mul_f32 v[10:11], v[10:11], v[66:67]
	v_pk_mul_f32 v[12:13], v[12:13], v[46:47] op_sel_hi:[1,0]
	v_pk_fma_f32 v[2:3], v[10:11], v[2:3], v[76:77]
	v_pk_mul_f32 v[10:11], v[38:39], v[50:51] op_sel_hi:[1,0]
	s_nop 0
	v_pk_mul_f32 v[10:11], v[10:11], v[72:73]
	s_nop 0
	v_pk_fma_f32 v[6:7], v[10:11], v[6:7], v[88:89]
	v_cvt_pk_bf16_f32 v3, v3, v7
	v_cvt_pk_bf16_f32 v2, v2, v6
	global_store_dwordx2 v[8:9], v[2:3], off offset:512
	v_lshl_add_u64 v[2:3], v[68:69], 0, v[108:109]
	global_load_dwordx4 v[36:39], v[100:101], off offset:2048
	global_load_dwordx4 v[64:67], v[2:3], off
	global_load_dwordx4 v[70:73], v[62:63], off offset:2048
	v_pk_mul_f32 v[10:11], v[56:57], v[46:47] op_sel_hi:[1,0]
	s_waitcnt vmcnt(2)
	v_mov_b32_e32 v42, v36
	s_waitcnt vmcnt(1)
	v_mov_b32_e32 v2, v64
	v_mov_b32_e32 v3, v66
	v_mov_b32_e32 v43, v38
	v_pk_add_f32 v[2:3], v[2:3], 1.0 op_sel_hi:[1,0]
	v_mov_b32_e32 v66, v65
	v_pk_mul_f32 v[10:11], v[10:11], v[42:43]
	s_waitcnt vmcnt(0)
	v_mov_b32_e32 v56, v70
	v_mov_b32_e32 v57, v72
	v_mov_b32_e32 v38, v37
	v_pk_add_f32 v[6:7], v[66:67], 1.0 op_sel_hi:[1,0]
	v_pk_fma_f32 v[10:11], v[10:11], v[2:3], v[56:57]
	v_pk_mul_f32 v[36:37], v[40:41], v[38:39]
	v_mov_b32_e32 v72, v71
	v_pk_fma_f32 v[36:37], v[36:37], v[6:7], v[72:73]
	v_cvt_pk_bf16_f32 v11, v11, v37
	v_cvt_pk_bf16_f32 v10, v10, v36
	global_store_dwordx2 v[58:59], v[10:11], off offset:1024
	v_pk_mul_f32 v[10:11], v[52:53], v[44:45] op_sel_hi:[1,0]
	v_pk_mul_f32 v[36:37], v[48:49], v[44:45] op_sel_hi:[1,0]
	v_pk_mul_f32 v[10:11], v[10:11], v[42:43]
	v_pk_mul_f32 v[36:37], v[36:37], v[38:39]
	v_pk_fma_f32 v[10:11], v[10:11], v[2:3], v[56:57]
	v_pk_fma_f32 v[36:37], v[36:37], v[6:7], v[72:73]
	v_cvt_pk_bf16_f32 v11, v11, v37
	v_cvt_pk_bf16_f32 v10, v10, v36
	global_store_dwordx2 v[0:1], v[10:11], off offset:1024
	v_pk_mul_f32 v[10:11], v[30:31], v[54:55] op_sel_hi:[1,0]
	v_pk_mul_f32 v[26:27], v[26:27], v[38:39]
	v_pk_mul_f32 v[10:11], v[10:11], v[42:43]
	v_pk_fma_f32 v[26:27], v[26:27], v[6:7], v[72:73]
	v_pk_fma_f32 v[10:11], v[10:11], v[2:3], v[56:57]
	s_nop 0
	v_cvt_pk_bf16_f32 v11, v11, v27
	v_cvt_pk_bf16_f32 v10, v10, v26
	global_store_dwordx2 v[4:5], v[10:11], off offset:1024
	v_pk_mul_f32 v[10:11], v[34:35], v[50:51] op_sel_hi:[1,0]
	s_nop 0
	v_pk_mul_f32 v[10:11], v[10:11], v[42:43]
	s_nop 0
	v_pk_fma_f32 v[2:3], v[10:11], v[2:3], v[56:57]
	v_pk_mul_f32 v[10:11], v[28:29], v[50:51] op_sel_hi:[1,0]
	s_nop 0
	v_pk_mul_f32 v[10:11], v[10:11], v[38:39]
	s_nop 0
	v_pk_fma_f32 v[6:7], v[10:11], v[6:7], v[72:73]
	v_cvt_pk_bf16_f32 v3, v3, v7
	v_cvt_pk_bf16_f32 v2, v2, v6
	global_store_dwordx2 v[8:9], v[2:3], off offset:1024
	v_lshl_add_u64 v[2:3], v[68:69], 0, v[110:111]
	global_load_dwordx4 v[26:29], v[100:101], off offset:3072
	global_load_dwordx4 v[34:37], v[2:3], off
	global_load_dwordx4 v[38:41], v[62:63], off offset:3072
	v_pk_mul_f32 v[10:11], v[32:33], v[46:47] op_sel_hi:[1,0]
	s_waitcnt vmcnt(2)
	v_mov_b32_e32 v30, v26
	s_waitcnt vmcnt(1)
	v_mov_b32_e32 v2, v34
	v_mov_b32_e32 v3, v36
	v_mov_b32_e32 v31, v28
	v_pk_add_f32 v[2:3], v[2:3], 1.0 op_sel_hi:[1,0]
	v_mov_b32_e32 v36, v35
	v_pk_mul_f32 v[10:11], v[10:11], v[30:31]
	s_waitcnt vmcnt(0)
	v_mov_b32_e32 v32, v38
	v_mov_b32_e32 v33, v40
	v_mov_b32_e32 v28, v27
	v_pk_add_f32 v[6:7], v[36:37], 1.0 op_sel_hi:[1,0]
	v_pk_fma_f32 v[10:11], v[10:11], v[2:3], v[32:33]
	v_pk_mul_f32 v[12:13], v[12:13], v[28:29]
	v_mov_b32_e32 v40, v39
	v_pk_fma_f32 v[12:13], v[12:13], v[6:7], v[40:41]
	v_cvt_pk_bf16_f32 v11, v11, v13
	v_cvt_pk_bf16_f32 v10, v10, v12
	global_store_dwordx2 v[58:59], v[10:11], off offset:1536
	v_pk_mul_f32 v[10:11], v[24:25], v[44:45] op_sel_hi:[1,0]
	v_pk_mul_f32 v[12:13], v[20:21], v[44:45] op_sel_hi:[1,0]
	v_pk_mul_f32 v[10:11], v[10:11], v[30:31]
	v_pk_mul_f32 v[12:13], v[12:13], v[28:29]
	v_pk_fma_f32 v[10:11], v[10:11], v[2:3], v[32:33]
	v_pk_fma_f32 v[12:13], v[12:13], v[6:7], v[40:41]
	v_cvt_pk_bf16_f32 v11, v11, v13
	v_cvt_pk_bf16_f32 v10, v10, v12
	global_store_dwordx2 v[0:1], v[10:11], off offset:1536
	v_pk_mul_f32 v[0:1], v[22:23], v[54:55] op_sel_hi:[1,0]
	v_pk_mul_f32 v[10:11], v[16:17], v[54:55] op_sel_hi:[1,0]
	v_pk_mul_f32 v[0:1], v[0:1], v[30:31]
	v_pk_mul_f32 v[10:11], v[10:11], v[28:29]
	v_pk_fma_f32 v[0:1], v[0:1], v[2:3], v[32:33]
	v_pk_fma_f32 v[10:11], v[10:11], v[6:7], v[40:41]
	v_cvt_pk_bf16_f32 v1, v1, v11
	v_cvt_pk_bf16_f32 v0, v0, v10
	global_store_dwordx2 v[4:5], v[0:1], off offset:1536
	v_pk_mul_f32 v[0:1], v[14:15], v[50:51] op_sel_hi:[1,0]
	s_nop 0
	v_pk_mul_f32 v[0:1], v[0:1], v[30:31]
	s_nop 0
	v_pk_fma_f32 v[0:1], v[0:1], v[2:3], v[32:33]
	v_pk_mul_f32 v[2:3], v[18:19], v[50:51] op_sel_hi:[1,0]
	v_and_b32_sdwa v4, v1, v218 dst_sel:DWORD dst_unused:UNUSED_PAD src0_sel:WORD_1 src1_sel:DWORD
	v_pk_mul_f32 v[2:3], v[2:3], v[28:29]
	v_and_b32_sdwa v5, v0, v218 dst_sel:DWORD dst_unused:UNUSED_PAD src0_sel:WORD_1 src1_sel:DWORD
	v_pk_fma_f32 v[2:3], v[2:3], v[6:7], v[40:41]
	v_add3_u32 v0, v0, v5, s80
	v_add3_u32 v1, v1, v4, s80
	v_and_b32_sdwa v4, v3, v218 dst_sel:DWORD dst_unused:UNUSED_PAD src0_sel:WORD_1 src1_sel:DWORD
	v_and_b32_sdwa v5, v2, v218 dst_sel:DWORD dst_unused:UNUSED_PAD src0_sel:WORD_1 src1_sel:DWORD
	v_add3_u32 v3, v3, v4, s80
	v_add3_u32 v2, v2, v5, s80
	v_and_b32_e32 v3, 0xffff0000, v3
	v_and_b32_e32 v2, 0xffff0000, v2
	v_or_b32_sdwa v1, v3, v1 dst_sel:DWORD dst_unused:UNUSED_PAD src0_sel:DWORD src1_sel:WORD_1
	v_or_b32_sdwa v0, v2, v0 dst_sel:DWORD dst_unused:UNUSED_PAD src0_sel:DWORD src1_sel:WORD_1
	global_store_dwordx2 v[8:9], v[0:1], off offset:1536
	s_branch .LBB0_27

.LBB0_34:
	v_cmp_gt_i32_e32 vcc, 0, v40
	v_min_i32_e32 v0, 0x4000, v26
	v_mov_b32_e32 v2, s23
	v_mov_b32_e32 v3, s89
	v_ashrrev_i32_e32 v31, 13, v0
	v_cndmask_b32_e32 v1, 0, v27, vcc
	v_cndmask_b32_e32 v0, v40, v26, vcc
	v_cndmask_b32_e32 v3, v2, v3, vcc
	v_mov_b32_e32 v2, s22
	v_mov_b32_e32 v4, s88
	v_cndmask_b32_e32 v2, v2, v4, vcc
	v_lshlrev_b64 v[0:1], 12, v[0:1]
	v_lshl_add_u64 v[0:1], v[2:3], 0, v[0:1]
	v_lshl_add_u64 v[36:37], v[0:1], 0, v[192:193]
	global_load_dwordx4 v[12:15], v[36:37], off nt
	global_load_dwordx4 v[8:11], v[36:37], off offset:1024 nt
	global_load_dwordx4 v[4:7], v[36:37], off offset:2048 nt
	global_load_dwordx4 v[0:3], v[36:37], off offset:3072 nt
	global_load_dwordx2 v[56:57], v[28:29], off
	global_load_dwordx2 v[64:65], v[28:29], off offset:512
	global_load_dwordx2 v[72:73], v[28:29], off offset:1024
	global_load_dwordx2 v[80:81], v[28:29], off offset:1536
	v_mul_hi_i32_i24_e32 v39, 0x6000, v31
	v_mul_i32_i24_e32 v38, 0x6000, v31
	v_lshl_add_u64 v[38:39], s[90:91], 0, v[38:39]
	s_waitcnt vmcnt(11)
	v_lshl_add_u64 v[52:53], v[38:39], 0, v[192:193]
	v_lshl_add_u64 v[76:77], v[52:53], 0, s[34:35]
	v_add_co_u32_e32 v52, vcc, s24, v52
	global_load_dwordx4 v[48:51], v[16:17], off
	s_nop 0
	v_addc_co_u32_e32 v53, vcc, 0, v53, vcc
	global_load_dwordx4 v[52:55], v[52:53], off
	s_mov_b32 s4, 0xf823c000
	v_add_u32_e32 v40, s20, v40
	v_lshl_add_u64 v[26:27], v[26:27], 0, s[20:21]
	s_waitcnt vmcnt(5)
	v_and_b32_e32 v39, 0xffff0000, v56
	s_waitcnt vmcnt(4)
	v_and_b32_e32 v85, 0xffff0000, v64
	v_lshlrev_b32_e32 v38, 16, v56
	v_lshlrev_b32_e32 v84, 16, v64
	v_mov_b32_e32 v66, v39
	v_mov_b32_e32 v67, v85
	v_lshlrev_b32_e32 v82, 16, v57
	v_and_b32_e32 v87, 0xffff0000, v65
	v_lshlrev_b32_e32 v86, 16, v65
	v_mov_b32_e32 v64, v38
	v_mov_b32_e32 v65, v84
	v_pk_mul_f32 v[66:67], v[66:67], v[66:67]
	v_and_b32_e32 v83, 0xffff0000, v57
	global_load_dwordx4 v[56:59], v[16:17], off offset:1024
	global_load_dwordx4 v[60:63], v[76:77], off offset:1024
	v_pk_fma_f32 v[64:65], v[64:65], v[64:65], v[66:67]
	v_mov_b32_e32 v66, v82
	v_mov_b32_e32 v67, v86
	v_mov_b32_e32 v68, v83
	v_mov_b32_e32 v69, v87
	v_pk_fma_f32 v[64:65], v[66:67], v[66:67], v[64:65]
	s_waitcnt vmcnt(5)
	v_and_b32_e32 v91, 0xffff0000, v72
	v_pk_fma_f32 v[88:89], v[68:69], v[68:69], v[64:65]
	global_load_dwordx4 v[64:67], v[16:17], off offset:2048
	global_load_dwordx4 v[68:71], v[76:77], off offset:2048
	v_lshlrev_b32_e32 v90, 16, v72
	v_and_b32_e32 v93, 0xffff0000, v73
	v_lshlrev_b32_e32 v92, 16, v73
	global_load_dwordx4 v[72:75], v[16:17], off offset:3072
	s_nop 0
	global_load_dwordx4 v[76:79], v[76:77], off offset:3072
	s_waitcnt vmcnt(8)
	v_and_b32_e32 v95, 0xffff0000, v80
	v_lshlrev_b32_e32 v94, 16, v80
	v_mov_b32_e32 v98, v91
	v_mov_b32_e32 v99, v95
	v_and_b32_e32 v97, 0xffff0000, v81
	v_lshlrev_b32_e32 v96, 16, v81
	v_mov_b32_e32 v80, v90
	v_mov_b32_e32 v81, v94
	v_pk_mul_f32 v[98:99], v[98:99], v[98:99]
	v_mov_b32_e32 v100, v93
	v_pk_fma_f32 v[80:81], v[80:81], v[80:81], v[98:99]
	v_mov_b32_e32 v98, v92
	v_mov_b32_e32 v99, v96
	v_mov_b32_e32 v101, v97
	v_pk_fma_f32 v[80:81], v[98:99], v[98:99], v[80:81]
	v_add_f32_e32 v33, v88, v89
	v_pk_fma_f32 v[80:81], v[100:101], v[100:101], v[80:81]
	s_nop 0
	v_add_f32_e32 v33, v33, v80
	v_add_f32_e32 v33, v33, v81
	s_nop 0
	s_nop 1
	v_add_f32_dpp v33, v33, v33 quad_perm:[1,0,3,2] row_mask:0xf bank_mask:0xf
	s_nop 1
	v_add_f32_dpp v33, v33, v33 quad_perm:[2,3,0,1] row_mask:0xf bank_mask:0xf
	s_nop 1
	v_add_f32_dpp v33, v33, v33 row_half_mirror row_mask:0xf bank_mask:0xf
	s_nop 1
	v_add_f32_dpp v33, v33, v33 row_mirror row_mask:0xf bank_mask:0xf
	s_nop 1
	v_mov_b32_e32 v35, v33
	s_nop 1
	v_permlane16_swap_b32_e32 v33, v35
	s_nop 1
	v_add_f32_e32 v33, v33, v35
	s_nop 1
	v_mov_b32_e32 v35, v33
	s_nop 1
	v_permlane32_swap_b32_e32 v33, v35
	s_nop 1
	v_add_f32_e32 v33, v33, v35
	s_nop 1
	v_fmamk_f32 v33, v33, 0x3a800000, v219
	v_cmp_gt_f32_e32 vcc, s25, v33
	v_mul_f32_e32 v35, 0x4b800000, v33
	s_nop 0
	v_cndmask_b32_e32 v33, v33, v35, vcc
	v_rsq_f32_e32 v33, v33
	s_nop 0
	v_mul_f32_e32 v35, 0x45800000, v33
	v_cndmask_b32_e32 v80, v33, v35, vcc
	v_pk_mul_f32 v[38:39], v[80:81], v[38:39] op_sel_hi:[0,1]
	s_waitcnt vmcnt(7)
	v_pk_mul_f32 v[38:39], v[48:49], v[38:39]
	v_pk_mul_f32 v[48:49], v[80:81], v[82:83] op_sel_hi:[0,1]
	v_pk_mul_f32 v[50:51], v[50:51], v[48:49]
	s_waitcnt vmcnt(6)
	v_pk_fma_f32 v[48:49], v[52:53], v[38:39], v[12:13]
	v_pk_mul_f32 v[12:13], v[80:81], v[84:85] op_sel_hi:[0,1]
	v_pk_fma_f32 v[50:51], v[54:55], v[50:51], v[14:15]
	s_waitcnt vmcnt(5)
	v_pk_mul_f32 v[12:13], v[56:57], v[12:13]
	v_pk_mul_f32 v[14:15], v[80:81], v[86:87] op_sel_hi:[0,1]
	v_pk_mul_f32 v[14:15], v[58:59], v[14:15]
	s_waitcnt vmcnt(4)
	v_pk_fma_f32 v[8:9], v[60:61], v[12:13], v[8:9]
	v_pk_mul_f32 v[12:13], v[80:81], v[90:91] op_sel_hi:[0,1]
	v_pk_fma_f32 v[10:11], v[62:63], v[14:15], v[10:11]
	s_waitcnt vmcnt(3)
	v_pk_mul_f32 v[12:13], v[12:13], v[64:65]
	v_pk_mul_f32 v[14:15], v[80:81], v[92:93] op_sel_hi:[0,1]
	v_pk_mul_f32 v[14:15], v[14:15], v[66:67]
	s_waitcnt vmcnt(2)
	v_pk_fma_f32 v[4:5], v[12:13], v[68:69], v[4:5]
	v_pk_mul_f32 v[12:13], v[80:81], v[94:95] op_sel_hi:[0,1]
	v_pk_fma_f32 v[6:7], v[14:15], v[70:71], v[6:7]
	s_waitcnt vmcnt(1)
	v_pk_mul_f32 v[12:13], v[12:13], v[72:73]
	v_pk_mul_f32 v[14:15], v[80:81], v[96:97] op_sel_hi:[0,1]
	v_pk_mul_f32 v[14:15], v[14:15], v[74:75]
	s_waitcnt vmcnt(0)
	v_pk_fma_f32 v[0:1], v[12:13], v[76:77], v[0:1]
	v_add_u32_e32 v12, 3, v31
	v_pk_fma_f32 v[2:3], v[14:15], v[78:79], v[2:3]
	global_store_dwordx4 v[36:37], v[48:51], off nt
	global_store_dwordx4 v[36:37], v[8:11], off offset:1024 nt
	global_store_dwordx4 v[36:37], v[4:7], off offset:2048 nt
	global_store_dwordx4 v[36:37], v[0:3], off offset:3072 nt
	v_mul_hi_i32_i24_e32 v13, 0x6000, v12
	v_mul_i32_i24_e32 v12, 0x6000, v12
	v_mov_b32_e32 v36, v49
	v_mov_b32_e32 v37, v9
	v_lshl_add_u64 v[14:15], s[96:97], 0, v[12:13]
	v_mov_b32_e32 v12, v48
	v_mov_b32_e32 v13, v8
	v_pk_mul_f32 v[36:37], v[36:37], v[36:37]
	v_mov_b32_e32 v38, v5
	v_pk_fma_f32 v[12:13], v[12:13], v[12:13], v[36:37]
	v_mov_b32_e32 v36, v50
	v_mov_b32_e32 v37, v10
	v_pk_fma_f32 v[12:13], v[36:37], v[36:37], v[12:13]
	v_mov_b32_e32 v36, v51
	v_mov_b32_e32 v37, v11
	v_mov_b32_e32 v39, v1
	v_pk_fma_f32 v[12:13], v[36:37], v[36:37], v[12:13]
	v_mov_b32_e32 v36, v4
	v_mov_b32_e32 v37, v0
	v_pk_mul_f32 v[38:39], v[38:39], v[38:39]
	v_add_f32_e32 v12, v12, v13
	v_pk_fma_f32 v[36:37], v[36:37], v[36:37], v[38:39]
	v_mov_b32_e32 v38, v6
	v_mov_b32_e32 v39, v2
	v_pk_fma_f32 v[36:37], v[38:39], v[38:39], v[36:37]
	v_mov_b32_e32 v38, v7
	v_mov_b32_e32 v39, v3
	v_pk_fma_f32 v[36:37], v[38:39], v[38:39], v[36:37]
	s_nop 0
	v_add_f32_e32 v12, v12, v36
	v_add_f32_e32 v12, v12, v37
	v_lshl_add_u64 v[36:37], v[14:15], 0, s[28:29]
	v_lshl_add_u64 v[38:39], v[36:37], 0, v[192:193]
	v_lshl_add_u64 v[14:15], v[14:15], 0, v[192:193]
	global_load_dwordx4 v[52:55], v[18:19], off
	global_load_dwordx4 v[56:59], v[38:39], off
	global_load_dwordx4 v[60:63], v[14:15], off
	v_mov_b32_e32 v38, v48
	v_mov_b32_e32 v39, v50
	v_mov_b32_e32 v50, v49
	s_nop 0
	s_nop 1
	v_add_f32_dpp v12, v12, v12 quad_perm:[1,0,3,2] row_mask:0xf bank_mask:0xf
	s_nop 1
	v_add_f32_dpp v12, v12, v12 quad_perm:[2,3,0,1] row_mask:0xf bank_mask:0xf
	s_nop 1
	v_add_f32_dpp v12, v12, v12 row_half_mirror row_mask:0xf bank_mask:0xf
	s_nop 1
	v_add_f32_dpp v12, v12, v12 row_mirror row_mask:0xf bank_mask:0xf
	s_nop 1
	v_mov_b32_e32 v13, v12
	s_nop 1
	v_permlane16_swap_b32_e32 v12, v13
	s_nop 1
	v_add_f32_e32 v12, v12, v13
	s_nop 1
	v_mov_b32_e32 v13, v12
	s_nop 1
	v_permlane32_swap_b32_e32 v12, v13
	s_nop 1
	v_add_f32_e32 v12, v12, v13
	s_nop 1
	v_fmamk_f32 v12, v12, 0x3a800000, v219
	v_cmp_gt_f32_e32 vcc, s25, v12
	v_mul_f32_e32 v13, 0x4b800000, v12
	s_waitcnt vmcnt(2)
	v_mov_b32_e32 v64, v52
	v_cndmask_b32_e32 v12, v12, v13, vcc
	v_rsq_f32_e32 v12, v12
	v_mov_b32_e32 v65, v54
	v_mov_b32_e32 v54, v53
	s_waitcnt vmcnt(0)
	v_mov_b32_e32 v67, v62
	v_mul_f32_e32 v13, 0x45800000, v12
	v_cndmask_b32_e32 v12, v12, v13, vcc
	v_pk_mul_f32 v[38:39], v[38:39], v[12:13] op_sel_hi:[1,0]
	v_pk_mul_f32 v[48:49], v[50:51], v[12:13] op_sel_hi:[1,0]
	v_pk_mul_f32 v[38:39], v[64:65], v[38:39]
	v_mov_b32_e32 v65, v58
	v_mov_b32_e32 v58, v57
	v_mov_b32_e32 v64, v56
	v_pk_mul_f32 v[48:49], v[54:55], v[48:49]
	v_pk_add_f32 v[50:51], v[58:59], 1.0 op_sel_hi:[1,0]
	v_mov_b32_e32 v62, v61
	v_pk_add_f32 v[64:65], v[64:65], 1.0 op_sel_hi:[1,0]
	v_mov_b32_e32 v66, v60
	v_pk_fma_f32 v[48:49], v[50:51], v[48:49], v[62:63]
	v_pk_fma_f32 v[38:39], v[64:65], v[38:39], v[66:67]
	v_and_b32_sdwa v33, v49, v218 dst_sel:DWORD dst_unused:UNUSED_PAD src0_sel:WORD_1 src1_sel:DWORD
	v_and_b32_sdwa v13, v39, v218 dst_sel:DWORD dst_unused:UNUSED_PAD src0_sel:WORD_1 src1_sel:DWORD
	v_cvt_pk_bf16_f32 v38, v38, v48
	v_add3_u32 v33, v49, v33, s80
	v_add3_u32 v13, v39, v13, s80
	v_and_b32_e32 v33, 0xffff0000, v33
	v_add_co_u32_e32 v48, vcc, s4, v28
	v_or_b32_sdwa v39, v33, v13 dst_sel:DWORD dst_unused:UNUSED_PAD src0_sel:DWORD src1_sel:WORD_1
	s_nop 0
	v_addc_co_u32_e32 v49, vcc, -1, v29, vcc
	global_store_dwordx2 v[48:49], v[38:39], off
	v_mov_b32_e32 v31, v193
	v_lshl_add_u64 v[38:39], v[36:37], 0, v[30:31]
	global_load_dwordx4 v[48:51], v[20:21], off
	global_load_dwordx4 v[52:55], v[38:39], off
	global_load_dwordx4 v[56:59], v[14:15], off offset:1024
	v_mov_b32_e32 v38, v8
	v_mov_b32_e32 v39, v10
	v_pk_mul_f32 v[38:39], v[38:39], v[12:13] op_sel_hi:[1,0]
	v_mov_b32_e32 v10, v9
	v_pk_mul_f32 v[8:9], v[10:11], v[12:13] op_sel_hi:[1,0]
	s_mov_b32 s4, 0xf823d000
	v_mov_b32_e32 v33, v193
	v_mov_b32_e32 v35, v193
	s_waitcnt vmcnt(2)
	v_mov_b32_e32 v60, v48
	v_mov_b32_e32 v61, v50
	v_pk_mul_f32 v[38:39], v[38:39], v[60:61]
	s_waitcnt vmcnt(1)
	v_mov_b32_e32 v60, v52
	v_mov_b32_e32 v61, v54
	v_pk_add_f32 v[60:61], v[60:61], 1.0 op_sel_hi:[1,0]
	s_waitcnt vmcnt(0)
	v_mov_b32_e32 v62, v56
	v_mov_b32_e32 v63, v58
	v_mov_b32_e32 v50, v49
	v_mov_b32_e32 v54, v53
	v_pk_fma_f32 v[38:39], v[38:39], v[60:61], v[62:63]
	v_pk_mul_f32 v[8:9], v[8:9], v[50:51]
	v_pk_add_f32 v[10:11], v[54:55], 1.0 op_sel_hi:[1,0]
	v_mov_b32_e32 v58, v57
	v_pk_fma_f32 v[8:9], v[8:9], v[10:11], v[58:59]
	v_and_b32_sdwa v11, v38, v218 dst_sel:DWORD dst_unused:UNUSED_PAD src0_sel:WORD_1 src1_sel:DWORD
	v_add3_u32 v13, v38, v11, s80
	v_and_b32_sdwa v31, v8, v218 dst_sel:DWORD dst_unused:UNUSED_PAD src0_sel:WORD_1 src1_sel:DWORD
	v_cvt_pk_bf16_f32 v11, v39, v9
	v_add3_u32 v8, v8, v31, s80
	v_and_b32_e32 v8, 0xffff0000, v8
	v_or_b32_sdwa v10, v8, v13 dst_sel:DWORD dst_unused:UNUSED_PAD src0_sel:DWORD src1_sel:WORD_1
	v_add_co_u32_e32 v8, vcc, s4, v28
	s_nop 1
	v_addc_co_u32_e32 v9, vcc, -1, v29, vcc
	global_store_dwordx2 v[8:9], v[10:11], off offset:-3584
	v_lshl_add_u64 v[10:11], v[36:37], 0, v[32:33]
	global_load_dwordx4 v[48:51], v[22:23], off
	global_load_dwordx4 v[52:55], v[10:11], off
	global_load_dwordx4 v[56:59], v[14:15], off offset:2048
	v_mov_b32_e32 v10, v4
	v_mov_b32_e32 v11, v6
	v_pk_mul_f32 v[10:11], v[10:11], v[12:13] op_sel_hi:[1,0]
	v_mov_b32_e32 v6, v5
	v_pk_mul_f32 v[4:5], v[6:7], v[12:13] op_sel_hi:[1,0]
	v_cmp_lt_i32_e32 vcc, s26, v40
	v_lshl_add_u64 v[28:29], v[28:29], 0, s[30:31]
	s_or_b64 s[2:3], vcc, s[2:3]
	s_waitcnt vmcnt(2)
	v_mov_b32_e32 v38, v48
	v_mov_b32_e32 v39, v50
	v_pk_mul_f32 v[10:11], v[10:11], v[38:39]
	s_waitcnt vmcnt(1)
	v_mov_b32_e32 v38, v52
	v_mov_b32_e32 v39, v54
	v_pk_add_f32 v[38:39], v[38:39], 1.0 op_sel_hi:[1,0]
	s_waitcnt vmcnt(0)
	v_mov_b32_e32 v60, v56
	v_mov_b32_e32 v61, v58
	v_mov_b32_e32 v50, v49
	v_mov_b32_e32 v54, v53
	v_pk_fma_f32 v[10:11], v[10:11], v[38:39], v[60:61]
	v_pk_mul_f32 v[4:5], v[4:5], v[50:51]
	v_pk_add_f32 v[6:7], v[54:55], 1.0 op_sel_hi:[1,0]
	v_mov_b32_e32 v58, v57
	v_pk_fma_f32 v[4:5], v[4:5], v[6:7], v[58:59]
	v_cvt_pk_bf16_f32 v4, v10, v4
	v_cvt_pk_bf16_f32 v5, v11, v5
	global_store_dwordx2 v[8:9], v[4:5], off offset:-3072
	v_lshl_add_u64 v[10:11], v[36:37], 0, v[34:35]
	global_load_dwordx4 v[4:7], v[24:25], off
	global_load_dwordx4 v[36:39], v[10:11], off
	global_load_dwordx4 v[48:51], v[14:15], off offset:3072
	v_mov_b32_e32 v10, v0
	v_mov_b32_e32 v11, v2
	v_pk_mul_f32 v[10:11], v[10:11], v[12:13] op_sel_hi:[1,0]
	v_mov_b32_e32 v2, v1
	v_pk_mul_f32 v[0:1], v[2:3], v[12:13] op_sel_hi:[1,0]
	s_waitcnt vmcnt(2)
	v_mov_b32_e32 v14, v4
	v_mov_b32_e32 v15, v6
	v_pk_mul_f32 v[10:11], v[10:11], v[14:15]
	s_waitcnt vmcnt(1)
	v_mov_b32_e32 v15, v38
	v_mov_b32_e32 v6, v5
	v_mov_b32_e32 v38, v37
	v_mov_b32_e32 v14, v36
	s_waitcnt vmcnt(0)
	v_mov_b32_e32 v53, v50
	v_pk_mul_f32 v[0:1], v[0:1], v[6:7]
	v_pk_add_f32 v[2:3], v[38:39], 1.0 op_sel_hi:[1,0]
	v_mov_b32_e32 v50, v49
	v_pk_add_f32 v[14:15], v[14:15], 1.0 op_sel_hi:[1,0]
	v_mov_b32_e32 v52, v48
	v_pk_fma_f32 v[0:1], v[0:1], v[2:3], v[50:51]
	v_pk_fma_f32 v[10:11], v[10:11], v[14:15], v[52:53]
	v_cvt_pk_bf16_f32 v1, v11, v1
	v_cvt_pk_bf16_f32 v0, v10, v0
	global_store_dwordx2 v[8:9], v[0:1], off offset:-2560
	s_andn2_b64 exec, exec, s[2:3]
	s_cbranch_execnz .LBB0_34

.LBB0_173:
	v_mov_b32_e32 v107, v193
	v_lshl_add_u64 v[28:29], v[0:1], 0, v[106:107]
	v_add_co_u32_e32 v4, vcc, 0x1000, v28
	v_min_i32_e32 v2, 0x4000, v104
	s_nop 0
	v_addc_co_u32_e32 v5, vcc, 0, v29, vcc
	v_ashrrev_i32_e32 v2, 13, v2
	v_add_co_u32_e32 v24, vcc, 0x2000, v28
	v_add_u32_e32 v2, s4, v2
	s_nop 0
	v_addc_co_u32_e32 v25, vcc, 0, v29, vcc
	v_mul_hi_i32_i24_e32 v123, 0x6000, v2
	v_mul_i32_i24_e32 v122, 0x6000, v2
	global_load_dwordx4 v[32:35], v[28:29], off nt
	global_load_dwordx4 v[16:19], v[28:29], off offset:1024 nt
	global_load_dwordx4 v[8:11], v[28:29], off offset:2048 nt
	global_load_dwordx4 v[0:3], v[28:29], off offset:3072 nt
	v_add_co_u32_e32 v28, vcc, 0x3000, v28
	v_lshlrev_b64 v[120:121], 11, v[104:105]
	s_nop 0
	v_addc_co_u32_e32 v29, vcc, 0, v29, vcc
	s_waitcnt vmcnt(4)
	v_lshl_add_u64 v[66:67], v[96:97], 0, v[120:121]
	global_load_dwordx4 v[36:39], v[4:5], off nt
	global_load_dwordx4 v[20:23], v[4:5], off offset:1024 nt
	global_load_dwordx4 v[12:15], v[4:5], off offset:2048 nt
	s_nop 0
	global_load_dwordx4 v[4:7], v[4:5], off offset:3072 nt
	s_nop 0
	global_load_dwordx4 v[60:63], v[24:25], off nt
	global_load_dwordx4 v[56:59], v[24:25], off offset:1024 nt
	global_load_dwordx4 v[40:43], v[24:25], off offset:2048 nt
	s_nop 0
	global_load_dwordx4 v[24:27], v[24:25], off offset:3072 nt
	s_nop 0
	global_load_dwordx4 v[52:55], v[28:29], off nt
	global_load_dwordx4 v[48:51], v[28:29], off offset:1024 nt
	global_load_dwordx4 v[44:47], v[28:29], off offset:2048 nt
	s_nop 0
	global_load_dwordx4 v[28:31], v[28:29], off offset:3072 nt
	s_nop 0
	global_load_dwordx2 v[72:73], v[66:67], off
	global_load_dwordx2 v[80:81], v[66:67], off offset:512
	global_load_dwordx2 v[88:89], v[66:67], off offset:1024
	global_load_dwordx2 v[126:127], v[66:67], off offset:1536
	v_add_u32_e32 v66, 1, v104
	v_ashrrev_i32_e32 v67, 31, v66
	v_lshlrev_b64 v[118:119], 11, v[66:67]
	v_lshl_add_u64 v[66:67], v[96:97], 0, v[118:119]
	global_load_dwordx2 v[74:75], v[66:67], off
	global_load_dwordx2 v[82:83], v[66:67], off offset:512
	global_load_dwordx2 v[90:91], v[66:67], off offset:1024
	global_load_dwordx2 v[162:163], v[66:67], off offset:1536
	v_add_u32_e32 v66, 2, v104
	v_ashrrev_i32_e32 v67, 31, v66
	v_lshlrev_b64 v[116:117], 11, v[66:67]
	v_lshl_add_u64 v[66:67], v[96:97], 0, v[116:117]
	global_load_dwordx2 v[76:77], v[66:67], off
	global_load_dwordx2 v[84:85], v[66:67], off offset:512
	global_load_dwordx2 v[92:93], v[66:67], off offset:1024
	global_load_dwordx2 v[132:133], v[66:67], off offset:1536
	v_add_u32_e32 v66, 3, v104
	v_ashrrev_i32_e32 v67, 31, v66
	v_lshlrev_b64 v[114:115], 11, v[66:67]
	v_lshl_add_u64 v[66:67], v[96:97], 0, v[114:115]
	global_load_dwordx2 v[78:79], v[66:67], off
	global_load_dwordx2 v[86:87], v[66:67], off offset:512
	global_load_dwordx2 v[178:179], v[66:67], off offset:1024
	global_load_dwordx2 v[138:139], v[66:67], off offset:1536
	v_lshl_add_u64 v[64:65], s[90:91], 0, v[122:123]
	v_lshl_add_u64 v[68:69], v[64:65], 0, v[106:107]
	s_mov_b64 s[0:1], 0x345a000
	v_lshl_add_u64 v[94:95], v[68:69], 0, s[0:1]
	s_mov_b32 s0, 0x345a000
	v_add_co_u32_e32 v68, vcc, s0, v68
	global_load_dwordx4 v[64:67], v[98:99], off
	s_nop 0
	v_addc_co_u32_e32 v69, vcc, 0, v69, vcc
	global_load_dwordx4 v[68:71], v[68:69], off
	s_mov_b32 s0, 0x358637bd
	s_mov_b32 s8, 0x3a800000
	s_mov_b32 s6, 0x800000
	v_mov_b32_e32 v111, v193
	v_mov_b32_e32 v113, v193
	s_add_i32 s5, s5, s93
	s_cmpk_gt_i32 s5, 0x3ff
	s_waitcnt vmcnt(17)
	v_and_b32_e32 v157, 0xffff0000, v72
	s_waitcnt vmcnt(16)
	v_and_b32_e32 v175, 0xffff0000, v80
	v_lshlrev_b32_e32 v156, 16, v72
	v_lshlrev_b32_e32 v174, 16, v80
	v_mov_b32_e32 v140, v157
	v_mov_b32_e32 v141, v175
	v_lshlrev_b32_e32 v168, 16, v73
	v_and_b32_e32 v177, 0xffff0000, v81
	v_lshlrev_b32_e32 v176, 16, v81
	v_mov_b32_e32 v80, v156
	v_mov_b32_e32 v81, v174
	v_pk_mul_f32 v[140:141], v[140:141], v[140:141]
	v_and_b32_e32 v169, 0xffff0000, v73
	s_waitcnt vmcnt(13)
	v_and_b32_e32 v165, 0xffff0000, v74
	v_pk_fma_f32 v[80:81], v[80:81], v[80:81], v[140:141]
	v_mov_b32_e32 v140, v168
	v_mov_b32_e32 v141, v176
	s_waitcnt vmcnt(12)
	v_and_b32_e32 v171, 0xffff0000, v82
	v_lshlrev_b32_e32 v164, 16, v74
	v_mov_b32_e32 v142, v169
	v_mov_b32_e32 v143, v177
	v_pk_fma_f32 v[80:81], v[140:141], v[140:141], v[80:81]
	v_lshlrev_b32_e32 v170, 16, v82
	v_and_b32_e32 v173, 0xffff0000, v83
	v_lshlrev_b32_e32 v172, 16, v83
	v_mov_b32_e32 v82, v165
	v_mov_b32_e32 v83, v171
	v_lshlrev_b32_e32 v166, 16, v75
	v_pk_fma_f32 v[188:189], v[142:143], v[142:143], v[80:81]
	v_mov_b32_e32 v80, v164
	v_mov_b32_e32 v81, v170
	v_pk_mul_f32 v[82:83], v[82:83], v[82:83]
	v_and_b32_e32 v167, 0xffff0000, v75
	s_waitcnt vmcnt(9)
	v_and_b32_e32 v137, 0xffff0000, v76
	v_pk_fma_f32 v[80:81], v[80:81], v[80:81], v[82:83]
	v_mov_b32_e32 v82, v166
	v_mov_b32_e32 v83, v172
	s_waitcnt vmcnt(8)
	v_and_b32_e32 v147, 0xffff0000, v84
	v_lshlrev_b32_e32 v136, 16, v76
	v_mov_b32_e32 v140, v167
	v_mov_b32_e32 v141, v173
	v_pk_fma_f32 v[80:81], v[82:83], v[82:83], v[80:81]
	v_lshlrev_b32_e32 v146, 16, v84
	v_mov_b32_e32 v82, v137
	v_mov_b32_e32 v83, v147
	v_lshlrev_b32_e32 v134, 16, v77
	v_pk_fma_f32 v[190:191], v[140:141], v[140:141], v[80:81]
	v_lshlrev_b32_e32 v144, 16, v85
	v_mov_b32_e32 v80, v136
	v_mov_b32_e32 v81, v146
	v_pk_mul_f32 v[82:83], v[82:83], v[82:83]
	v_and_b32_e32 v135, 0xffff0000, v77
	s_waitcnt vmcnt(5)
	v_and_b32_e32 v131, 0xffff0000, v78
	v_and_b32_e32 v145, 0xffff0000, v85
	v_pk_fma_f32 v[80:81], v[80:81], v[80:81], v[82:83]
	v_mov_b32_e32 v82, v134
	v_mov_b32_e32 v83, v144
	s_waitcnt vmcnt(4)
	v_and_b32_e32 v143, 0xffff0000, v86
	v_lshlrev_b32_e32 v130, 16, v78
	v_and_b32_e32 v129, 0xffff0000, v79
	v_lshlrev_b32_e32 v128, 16, v79
	global_load_dwordx4 v[72:75], v[98:99], off offset:1024
	global_load_dwordx4 v[76:79], v[94:95], off offset:1024
	v_mov_b32_e32 v84, v135
	v_mov_b32_e32 v85, v145
	v_pk_fma_f32 v[80:81], v[82:83], v[82:83], v[80:81]
	v_lshlrev_b32_e32 v142, 16, v86
	v_mov_b32_e32 v82, v131
	v_mov_b32_e32 v83, v143
	v_pk_fma_f32 v[158:159], v[84:85], v[84:85], v[80:81]
	v_lshlrev_b32_e32 v140, 16, v87
	v_mov_b32_e32 v80, v130
	v_mov_b32_e32 v81, v142
	v_pk_mul_f32 v[82:83], v[82:83], v[82:83]
	v_and_b32_e32 v141, 0xffff0000, v87
	v_pk_fma_f32 v[80:81], v[80:81], v[80:81], v[82:83]
	v_mov_b32_e32 v82, v128
	v_mov_b32_e32 v83, v140
	v_mov_b32_e32 v84, v129
	v_mov_b32_e32 v85, v141
	v_pk_fma_f32 v[80:81], v[82:83], v[82:83], v[80:81]
	v_and_b32_e32 v185, 0xffff0000, v88
	v_pk_fma_f32 v[160:161], v[84:85], v[84:85], v[80:81]
	global_load_dwordx4 v[80:83], v[98:99], off offset:2048
	global_load_dwordx4 v[84:87], v[94:95], off offset:2048
	v_lshlrev_b32_e32 v184, 16, v88
	v_and_b32_e32 v187, 0xffff0000, v89
	v_lshlrev_b32_e32 v186, 16, v89
	v_and_b32_e32 v181, 0xffff0000, v90
	v_lshlrev_b32_e32 v180, 16, v90
	v_and_b32_e32 v183, 0xffff0000, v91
	v_lshlrev_b32_e32 v182, 16, v91
	v_and_b32_e32 v155, 0xffff0000, v92
	v_lshlrev_b32_e32 v154, 16, v92
	v_and_b32_e32 v153, 0xffff0000, v93
	v_lshlrev_b32_e32 v152, 16, v93
	global_load_dwordx4 v[88:91], v[98:99], off offset:3072
	s_nop 0
	global_load_dwordx4 v[92:95], v[94:95], off offset:3072
	v_and_b32_e32 v205, 0xffff0000, v126
	s_waitcnt vmcnt(9)
	v_and_b32_e32 v151, 0xffff0000, v178
	v_lshlrev_b32_e32 v150, 16, v178
	v_and_b32_e32 v149, 0xffff0000, v179
	v_lshlrev_b32_e32 v148, 16, v179
	v_lshlrev_b32_e32 v204, 16, v126
	v_mov_b32_e32 v178, v185
	v_mov_b32_e32 v179, v205
	v_and_b32_e32 v225, 0xffff0000, v127
	v_lshlrev_b32_e32 v224, 16, v127
	v_mov_b32_e32 v126, v184
	v_mov_b32_e32 v127, v204
	v_pk_mul_f32 v[178:179], v[178:179], v[178:179]
	v_mov_b32_e32 v194, v187
	v_pk_fma_f32 v[126:127], v[126:127], v[126:127], v[178:179]
	v_mov_b32_e32 v178, v186
	v_mov_b32_e32 v179, v224
	v_pk_fma_f32 v[126:127], v[178:179], v[178:179], v[126:127]
	v_and_b32_e32 v179, 0xffff0000, v162
	v_mov_b32_e32 v195, v225
	v_lshlrev_b32_e32 v178, 16, v162
	v_mov_b32_e32 v232, v181
	v_mov_b32_e32 v233, v179
	v_pk_fma_f32 v[126:127], v[194:195], v[194:195], v[126:127]
	v_and_b32_e32 v195, 0xffff0000, v163
	v_lshlrev_b32_e32 v194, 16, v163
	v_mov_b32_e32 v162, v180
	v_mov_b32_e32 v163, v178
	v_pk_mul_f32 v[232:233], v[232:233], v[232:233]
	v_mov_b32_e32 v234, v183
	v_pk_fma_f32 v[162:163], v[162:163], v[162:163], v[232:233]
	v_mov_b32_e32 v232, v182
	v_mov_b32_e32 v233, v194
	v_mov_b32_e32 v235, v195
	v_pk_fma_f32 v[162:163], v[232:233], v[232:233], v[162:163]
	v_mov_b32_e32 v232, v190
	v_pk_fma_f32 v[162:163], v[234:235], v[234:235], v[162:163]
	v_mov_b32_e32 v233, v188
	v_mov_b32_e32 v188, v191
	v_pk_add_f32 v[188:189], v[232:233], v[188:189]
	v_mov_b32_e32 v190, v162
	v_mov_b32_e32 v191, v126
	v_pk_add_f32 v[188:189], v[188:189], v[190:191]
	v_mov_b32_e32 v126, v163
	v_pk_add_f32 v[126:127], v[188:189], v[126:127]
	v_mov_b32_e32 v163, v127
	v_mov_b32_e32 v162, v126
	s_nop 0
	v_add_f32_dpp v163, v163, v163 quad_perm:[1,0,3,2] row_mask:0xf bank_mask:0xf
	v_add_f32_dpp v162, v162, v162 quad_perm:[1,0,3,2] row_mask:0xf bank_mask:0xf
	s_nop 0
	v_add_f32_dpp v163, v163, v163 quad_perm:[2,3,0,1] row_mask:0xf bank_mask:0xf
	v_add_f32_dpp v162, v162, v162 quad_perm:[2,3,0,1] row_mask:0xf bank_mask:0xf
	s_nop 0
	v_add_f32_dpp v163, v163, v163 row_half_mirror row_mask:0xf bank_mask:0xf
	v_add_f32_dpp v162, v162, v162 row_half_mirror row_mask:0xf bank_mask:0xf
	s_nop 0
	v_add_f32_dpp v163, v163, v163 row_mirror row_mask:0xf bank_mask:0xf
	v_add_f32_dpp v162, v162, v162 row_mirror row_mask:0xf bank_mask:0xf
	s_nop 0
	v_mov_b32_e32 v127, v163
	v_mov_b32_e32 v126, v162
	s_nop 0
	v_permlane16_swap_b32_e32 v163, v127
	v_permlane16_swap_b32_e32 v162, v126
	s_nop 0
	v_add_f32_e32 v163, v163, v127
	v_add_f32_e32 v162, v162, v126
	s_nop 0
	v_mov_b32_e32 v127, v163
	v_mov_b32_e32 v126, v162
	s_nop 0
	v_permlane32_swap_b32_e32 v163, v127
	v_permlane32_swap_b32_e32 v162, v126
	s_nop 0
	v_add_f32_e32 v163, v163, v127
	v_add_f32_e32 v162, v162, v126
	s_nop 0
	v_mov_b64_e32 v[126:127], s[0:1]
	v_pk_fma_f32 v[162:163], v[162:163], s[8:9], v[126:127] op_sel_hi:[1,0,0]
	s_nop 0
	v_mul_f32_e32 v105, 0x4b800000, v163
	v_cmp_gt_f32_e64 s[0:1], s6, v163
	v_cmp_gt_f32_e32 vcc, s6, v162
	s_nop 0
	v_cndmask_b32_e64 v105, v163, v105, s[0:1]
	v_rsq_f32_e32 v105, v105
	s_nop 0
	v_mul_f32_e32 v109, 0x45800000, v105
	v_cndmask_b32_e64 v188, v105, v109, s[0:1]
	v_pk_mul_f32 v[156:157], v[188:189], v[156:157] op_sel_hi:[0,1]
	s_waitcnt vmcnt(7)
	v_pk_mul_f32 v[156:157], v[156:157], v[64:65]
	v_mul_f32_e32 v105, 0x4b800000, v162
	s_waitcnt vmcnt(6)
	v_pk_fma_f32 v[32:33], v[156:157], v[68:69], v[32:33]
	v_pk_mul_f32 v[156:157], v[188:189], v[168:169] op_sel_hi:[0,1]
	v_pk_mul_f32 v[156:157], v[156:157], v[66:67]
	v_cndmask_b32_e32 v105, v162, v105, vcc
	v_pk_fma_f32 v[34:35], v[156:157], v[70:71], v[34:35]
	v_pk_mul_f32 v[156:157], v[188:189], v[174:175] op_sel_hi:[0,1]
	s_waitcnt vmcnt(5)
	v_pk_mul_f32 v[156:157], v[156:157], v[72:73]
	v_rsq_f32_e32 v105, v105
	s_waitcnt vmcnt(4)
	v_pk_fma_f32 v[16:17], v[156:157], v[76:77], v[16:17]
	v_pk_mul_f32 v[156:157], v[188:189], v[176:177] op_sel_hi:[0,1]
	v_pk_mul_f32 v[156:157], v[156:157], v[74:75]
	v_mul_f32_e32 v109, 0x45800000, v105
	v_pk_fma_f32 v[18:19], v[156:157], v[78:79], v[18:19]
	v_pk_mul_f32 v[156:157], v[188:189], v[184:185] op_sel_hi:[0,1]
	s_waitcnt vmcnt(3)
	v_pk_mul_f32 v[156:157], v[156:157], v[80:81]
	v_mov_b32_e32 v168, v151
	s_waitcnt vmcnt(2)
	v_pk_fma_f32 v[8:9], v[156:157], v[84:85], v[8:9]
	v_pk_mul_f32 v[156:157], v[188:189], v[186:187] op_sel_hi:[0,1]
	v_pk_mul_f32 v[156:157], v[156:157], v[82:83]
	s_nop 0
	v_pk_fma_f32 v[10:11], v[156:157], v[86:87], v[10:11]
	v_pk_mul_f32 v[156:157], v[188:189], v[204:205] op_sel_hi:[0,1]
	s_waitcnt vmcnt(1)
	v_pk_mul_f32 v[156:157], v[156:157], v[88:89]
	s_waitcnt vmcnt(0)
	v_pk_fma_f32 v[0:1], v[156:157], v[92:93], v[0:1]
	v_pk_mul_f32 v[156:157], v[188:189], v[224:225] op_sel_hi:[0,1]
	v_pk_mul_f32 v[156:157], v[156:157], v[90:91]
	s_nop 0
	v_pk_fma_f32 v[2:3], v[156:157], v[94:95], v[2:3]
	v_cndmask_b32_e32 v156, v105, v109, vcc
	v_pk_mul_f32 v[162:163], v[156:157], v[164:165] op_sel_hi:[0,1]
	v_pk_mul_f32 v[162:163], v[162:163], v[64:65]
	v_and_b32_e32 v165, 0xffff0000, v133
	v_pk_fma_f32 v[36:37], v[162:163], v[68:69], v[36:37]
	v_pk_mul_f32 v[162:163], v[156:157], v[166:167] op_sel_hi:[0,1]
	v_pk_mul_f32 v[162:163], v[162:163], v[66:67]
	v_lshlrev_b32_e32 v164, 16, v133
	v_pk_fma_f32 v[38:39], v[162:163], v[70:71], v[38:39]
	v_pk_mul_f32 v[162:163], v[156:157], v[170:171] op_sel_hi:[0,1]
	v_pk_mul_f32 v[162:163], v[162:163], v[72:73]
	v_mov_b32_e32 v166, v153
	v_pk_fma_f32 v[20:21], v[162:163], v[76:77], v[20:21]
	v_pk_mul_f32 v[162:163], v[156:157], v[172:173] op_sel_hi:[0,1]
	v_pk_mul_f32 v[162:163], v[162:163], v[74:75]
	v_mov_b32_e32 v167, v165
	v_pk_fma_f32 v[22:23], v[162:163], v[78:79], v[22:23]
	v_pk_mul_f32 v[162:163], v[156:157], v[180:181] op_sel_hi:[0,1]
	v_pk_mul_f32 v[162:163], v[162:163], v[80:81]
	v_mov_b32_e32 v170, v149
	v_pk_fma_f32 v[12:13], v[162:163], v[84:85], v[12:13]
	v_pk_mul_f32 v[162:163], v[156:157], v[182:183] op_sel_hi:[0,1]
	v_pk_mul_f32 v[162:163], v[162:163], v[82:83]
	s_nop 0
	v_pk_fma_f32 v[14:15], v[162:163], v[86:87], v[14:15]
	v_pk_mul_f32 v[162:163], v[156:157], v[178:179] op_sel_hi:[0,1]
	v_pk_mul_f32 v[162:163], v[162:163], v[88:89]
	v_pk_mul_f32 v[156:157], v[156:157], v[194:195] op_sel_hi:[0,1]
	v_pk_fma_f32 v[4:5], v[162:163], v[92:93], v[4:5]
	v_pk_mul_f32 v[156:157], v[156:157], v[90:91]
	v_and_b32_e32 v163, 0xffff0000, v132
	v_pk_fma_f32 v[6:7], v[156:157], v[94:95], v[6:7]
	v_lshlrev_b32_e32 v162, 16, v132
	v_mov_b32_e32 v156, v155
	v_mov_b32_e32 v157, v163
	v_mov_b32_e32 v132, v154
	v_mov_b32_e32 v133, v162
	v_pk_mul_f32 v[156:157], v[156:157], v[156:157]
	s_nop 0
	v_pk_fma_f32 v[132:133], v[132:133], v[132:133], v[156:157]
	v_mov_b32_e32 v156, v152
	v_mov_b32_e32 v157, v164
	v_pk_fma_f32 v[132:133], v[156:157], v[156:157], v[132:133]
	v_and_b32_e32 v157, 0xffff0000, v138
	v_lshlrev_b32_e32 v156, 16, v138
	v_mov_b32_e32 v169, v157
	v_pk_fma_f32 v[166:167], v[166:167], v[166:167], v[132:133]
	v_and_b32_e32 v133, 0xffff0000, v139
	v_lshlrev_b32_e32 v132, 16, v139
	v_mov_b32_e32 v138, v150
	v_mov_b32_e32 v139, v156
	v_pk_mul_f32 v[168:169], v[168:169], v[168:169]
	v_mov_b32_e32 v171, v133
	v_pk_fma_f32 v[138:139], v[138:139], v[138:139], v[168:169]
	v_mov_b32_e32 v168, v148
	v_mov_b32_e32 v169, v132
	v_pk_fma_f32 v[138:139], v[168:169], v[168:169], v[138:139]
	v_mov_b32_e32 v168, v160
	v_pk_fma_f32 v[138:139], v[170:171], v[170:171], v[138:139]
	v_mov_b32_e32 v169, v158
	v_mov_b32_e32 v158, v161
	v_pk_add_f32 v[158:159], v[168:169], v[158:159]
	v_mov_b32_e32 v160, v138
	v_mov_b32_e32 v161, v166
	v_pk_add_f32 v[158:159], v[158:159], v[160:161]
	v_mov_b32_e32 v166, v139
	v_pk_add_f32 v[138:139], v[158:159], v[166:167]
	s_nop 0
	s_nop 1
	v_add_f32_dpp v139, v139, v139 quad_perm:[1,0,3,2] row_mask:0xf bank_mask:0xf
	v_add_f32_dpp v138, v138, v138 quad_perm:[1,0,3,2] row_mask:0xf bank_mask:0xf
	s_nop 0
	v_add_f32_dpp v139, v139, v139 quad_perm:[2,3,0,1] row_mask:0xf bank_mask:0xf
	v_add_f32_dpp v138, v138, v138 quad_perm:[2,3,0,1] row_mask:0xf bank_mask:0xf
	s_nop 0
	v_add_f32_dpp v139, v139, v139 row_half_mirror row_mask:0xf bank_mask:0xf
	v_add_f32_dpp v138, v138, v138 row_half_mirror row_mask:0xf bank_mask:0xf
	s_nop 0
	v_add_f32_dpp v139, v139, v139 row_mirror row_mask:0xf bank_mask:0xf
	v_add_f32_dpp v138, v138, v138 row_mirror row_mask:0xf bank_mask:0xf
	s_nop 0
	v_mov_b32_e32 v207, v139
	v_mov_b32_e32 v158, v138
	s_nop 0
	v_permlane16_swap_b32_e32 v139, v207
	v_permlane16_swap_b32_e32 v138, v158
	s_nop 0
	v_add_f32_e32 v139, v139, v207
	v_add_f32_e32 v138, v138, v158
	s_nop 0
	v_mov_b32_e32 v207, v139
	v_mov_b32_e32 v158, v138
	s_nop 0
	v_permlane32_swap_b32_e32 v139, v207
	v_permlane32_swap_b32_e32 v138, v158
	s_nop 0
	v_add_f32_e32 v139, v139, v207
	v_add_f32_e32 v138, v138, v158
	s_nop 0
	s_nop 0
	v_pk_fma_f32 v[138:139], v[138:139], s[8:9], v[126:127] op_sel_hi:[1,0,0]
	s_nop 0
	v_mul_f32_e32 v105, 0x4b800000, v139
	v_cmp_gt_f32_e64 s[0:1], s6, v139
	v_cmp_gt_f32_e32 vcc, s6, v138
	s_nop 0
	v_cndmask_b32_e64 v105, v139, v105, s[0:1]
	v_rsq_f32_e32 v105, v105
	s_nop 0
	v_mul_f32_e32 v109, 0x45800000, v105
	v_cndmask_b32_e64 v158, v105, v109, s[0:1]
	v_pk_mul_f32 v[134:135], v[158:159], v[134:135] op_sel_hi:[0,1]
	v_pk_mul_f32 v[134:135], v[66:67], v[134:135]
	v_mul_f32_e32 v105, 0x4b800000, v138
	v_pk_fma_f32 v[62:63], v[134:135], v[70:71], v[62:63]
	v_pk_mul_f32 v[134:135], v[158:159], v[146:147] op_sel_hi:[0,1]
	v_pk_mul_f32 v[134:135], v[134:135], v[72:73]
	v_cndmask_b32_e32 v105, v138, v105, vcc
	v_pk_fma_f32 v[56:57], v[134:135], v[76:77], v[56:57]
	v_pk_mul_f32 v[134:135], v[158:159], v[144:145] op_sel_hi:[0,1]
	v_pk_mul_f32 v[134:135], v[134:135], v[74:75]
	v_rsq_f32_e32 v105, v105
	v_pk_fma_f32 v[58:59], v[134:135], v[78:79], v[58:59]
	v_pk_mul_f32 v[134:135], v[158:159], v[154:155] op_sel_hi:[0,1]
	v_pk_mul_f32 v[134:135], v[134:135], v[80:81]
	v_mul_f32_e32 v109, 0x45800000, v105
	v_pk_fma_f32 v[40:41], v[134:135], v[84:85], v[40:41]
	v_pk_mul_f32 v[134:135], v[158:159], v[152:153] op_sel_hi:[0,1]
	v_pk_mul_f32 v[134:135], v[134:135], v[82:83]
	v_pk_mul_f32 v[136:137], v[158:159], v[136:137] op_sel_hi:[0,1]
	v_pk_fma_f32 v[42:43], v[134:135], v[86:87], v[42:43]
	v_pk_mul_f32 v[134:135], v[158:159], v[162:163] op_sel_hi:[0,1]
	v_pk_mul_f32 v[134:135], v[134:135], v[88:89]
	v_pk_mul_f32 v[136:137], v[64:65], v[136:137]
	v_pk_fma_f32 v[24:25], v[134:135], v[92:93], v[24:25]
	v_pk_mul_f32 v[134:135], v[158:159], v[164:165] op_sel_hi:[0,1]
	v_pk_mul_f32 v[134:135], v[134:135], v[90:91]
	s_movk_i32 s0, 0x1000
	v_pk_fma_f32 v[26:27], v[134:135], v[94:95], v[26:27]
	v_cndmask_b32_e32 v134, v105, v109, vcc
	v_pk_mul_f32 v[130:131], v[134:135], v[130:131] op_sel_hi:[0,1]
	v_pk_mul_f32 v[64:65], v[64:65], v[130:131]
	v_pk_fma_f32 v[60:61], v[68:69], v[136:137], v[60:61]
	v_pk_fma_f32 v[52:53], v[68:69], v[64:65], v[52:53]
	v_pk_mul_f32 v[64:65], v[134:135], v[128:129] op_sel_hi:[0,1]
	v_pk_mul_f32 v[64:65], v[66:67], v[64:65]
	v_mov_b32_e32 v109, v193
	v_pk_fma_f32 v[54:55], v[70:71], v[64:65], v[54:55]
	v_pk_mul_f32 v[64:65], v[134:135], v[142:143] op_sel_hi:[0,1]
	v_pk_mul_f32 v[64:65], v[72:73], v[64:65]
	v_mov_b32_e32 v70, v9
	v_pk_fma_f32 v[48:49], v[64:65], v[76:77], v[48:49]
	v_pk_mul_f32 v[64:65], v[134:135], v[140:141] op_sel_hi:[0,1]
	v_pk_mul_f32 v[64:65], v[64:65], v[74:75]
	v_mov_b32_e32 v71, v1
	v_pk_fma_f32 v[50:51], v[64:65], v[78:79], v[50:51]
	v_pk_mul_f32 v[64:65], v[134:135], v[150:151] op_sel_hi:[0,1]
	v_pk_mul_f32 v[64:65], v[64:65], v[80:81]
	v_pk_mul_f32 v[70:71], v[70:71], v[70:71]
	v_pk_fma_f32 v[44:45], v[64:65], v[84:85], v[44:45]
	v_pk_mul_f32 v[64:65], v[134:135], v[148:149] op_sel_hi:[0,1]
	v_pk_mul_f32 v[64:65], v[64:65], v[82:83]
	v_mov_b32_e32 v72, v37
	v_pk_fma_f32 v[46:47], v[64:65], v[86:87], v[46:47]
	v_pk_mul_f32 v[64:65], v[134:135], v[156:157] op_sel_hi:[0,1]
	v_pk_mul_f32 v[64:65], v[64:65], v[88:89]
	v_mov_b32_e32 v73, v21
	v_pk_fma_f32 v[28:29], v[64:65], v[92:93], v[28:29]
	v_pk_mul_f32 v[64:65], v[134:135], v[132:133] op_sel_hi:[0,1]
	v_pk_mul_f32 v[64:65], v[64:65], v[90:91]
	v_pk_mul_f32 v[72:73], v[72:73], v[72:73]
	v_pk_fma_f32 v[30:31], v[64:65], v[94:95], v[30:31]
	v_lshl_add_u64 v[64:65], v[124:125], 0, v[106:107]
	v_add_co_u32_e32 v66, vcc, s0, v64
	s_movk_i32 s0, 0x2000
	s_nop 0
	v_addc_co_u32_e32 v67, vcc, 0, v65, vcc
	v_add_co_u32_e32 v68, vcc, s0, v64
	global_store_dwordx4 v[64:65], v[32:35], off nt
	global_store_dwordx4 v[64:65], v[16:19], off offset:1024 nt
	global_store_dwordx4 v[64:65], v[8:11], off offset:2048 nt
	global_store_dwordx4 v[64:65], v[0:3], off offset:3072 nt
	v_addc_co_u32_e32 v69, vcc, 0, v65, vcc
	global_store_dwordx4 v[68:69], v[36:39], off offset:-4096 nt
	global_store_dwordx4 v[66:67], v[20:23], off offset:1024 nt
	global_store_dwordx4 v[66:67], v[12:15], off offset:2048 nt
	global_store_dwordx4 v[66:67], v[4:7], off offset:3072 nt
	global_store_dwordx4 v[68:69], v[60:63], off nt
	global_store_dwordx4 v[68:69], v[56:59], off offset:1024 nt
	global_store_dwordx4 v[68:69], v[40:43], off offset:2048 nt
	global_store_dwordx4 v[68:69], v[24:27], off offset:3072 nt
	v_mov_b32_e32 v68, v33
	v_mov_b32_e32 v69, v17
	v_mov_b32_e32 v66, v32
	v_mov_b32_e32 v67, v16
	v_pk_mul_f32 v[68:69], v[68:69], v[68:69]
	v_mov_b32_e32 v74, v13
	v_pk_fma_f32 v[66:67], v[66:67], v[66:67], v[68:69]
	v_mov_b32_e32 v68, v34
	v_mov_b32_e32 v69, v18
	v_pk_fma_f32 v[66:67], v[68:69], v[68:69], v[66:67]
	v_mov_b32_e32 v68, v35
	v_mov_b32_e32 v69, v19
	v_pk_fma_f32 v[66:67], v[68:69], v[68:69], v[66:67]
	v_mov_b32_e32 v68, v8
	v_mov_b32_e32 v69, v0
	v_pk_fma_f32 v[68:69], v[68:69], v[68:69], v[70:71]
	v_mov_b32_e32 v70, v10
	v_mov_b32_e32 v71, v2
	v_pk_fma_f32 v[68:69], v[70:71], v[70:71], v[68:69]
	v_mov_b32_e32 v70, v11
	v_mov_b32_e32 v71, v3
	v_pk_fma_f32 v[68:69], v[70:71], v[70:71], v[68:69]
	v_mov_b32_e32 v70, v36
	v_mov_b32_e32 v71, v20
	v_pk_fma_f32 v[70:71], v[70:71], v[70:71], v[72:73]
	v_mov_b32_e32 v72, v38
	v_mov_b32_e32 v73, v22
	v_pk_fma_f32 v[70:71], v[72:73], v[72:73], v[70:71]
	v_mov_b32_e32 v72, v39
	v_mov_b32_e32 v73, v23
	v_mov_b32_e32 v75, v5
	v_pk_fma_f32 v[70:71], v[72:73], v[72:73], v[70:71]
	v_mov_b32_e32 v72, v12
	v_mov_b32_e32 v73, v4
	v_pk_mul_f32 v[74:75], v[74:75], v[74:75]
	v_add_co_u32_e32 v64, vcc, s73, v64
	v_pk_fma_f32 v[72:73], v[72:73], v[72:73], v[74:75]
	v_mov_b32_e32 v74, v14
	v_mov_b32_e32 v75, v6
	v_pk_fma_f32 v[72:73], v[74:75], v[74:75], v[72:73]
	v_mov_b32_e32 v74, v15
	v_mov_b32_e32 v75, v7
	v_pk_fma_f32 v[72:73], v[74:75], v[74:75], v[72:73]
	v_mov_b32_e32 v74, v70
	v_mov_b32_e32 v75, v66
	v_mov_b32_e32 v66, v71
	v_pk_add_f32 v[66:67], v[74:75], v[66:67]
	v_mov_b32_e32 v70, v72
	v_mov_b32_e32 v71, v68
	v_pk_add_f32 v[66:67], v[66:67], v[70:71]
	v_mov_b32_e32 v68, v73
	v_pk_add_f32 v[66:67], v[66:67], v[68:69]
	v_addc_co_u32_e32 v65, vcc, 0, v65, vcc
	global_store_dwordx4 v[64:65], v[52:55], off nt
	global_store_dwordx4 v[64:65], v[48:51], off offset:1024 nt
	global_store_dwordx4 v[64:65], v[44:47], off offset:2048 nt
	global_store_dwordx4 v[64:65], v[28:31], off offset:3072 nt
	v_lshl_add_u64 v[64:65], s[96:97], 0, v[122:123]
	s_mov_b64 s[0:1], 0x3000
	v_lshl_add_u64 v[76:77], v[64:65], 0, s[0:1]
	v_mov_b32_e32 v70, v41
	v_mov_b32_e32 v71, v25
	v_pk_mul_f32 v[70:71], v[70:71], v[70:71]
	v_mov_b32_e32 v72, v53
	v_mov_b32_e32 v73, v49
	v_pk_mul_f32 v[72:73], v[72:73], v[72:73]
	v_mov_b32_e32 v74, v45
	v_mov_b32_e32 v75, v29
	v_pk_mul_f32 v[74:75], v[74:75], v[74:75]
	v_lshl_add_u64 v[86:87], v[102:103], 0, v[120:121]
	s_nop 0
	s_nop 1
	v_add_f32_dpp v67, v67, v67 quad_perm:[1,0,3,2] row_mask:0xf bank_mask:0xf
	v_add_f32_dpp v66, v66, v66 quad_perm:[1,0,3,2] row_mask:0xf bank_mask:0xf
	s_nop 0
	v_add_f32_dpp v67, v67, v67 quad_perm:[2,3,0,1] row_mask:0xf bank_mask:0xf
	v_add_f32_dpp v66, v66, v66 quad_perm:[2,3,0,1] row_mask:0xf bank_mask:0xf
	s_nop 0
	v_add_f32_dpp v67, v67, v67 row_half_mirror row_mask:0xf bank_mask:0xf
	v_add_f32_dpp v66, v66, v66 row_half_mirror row_mask:0xf bank_mask:0xf
	s_nop 0
	v_add_f32_dpp v67, v67, v67 row_mirror row_mask:0xf bank_mask:0xf
	v_add_f32_dpp v66, v66, v66 row_mirror row_mask:0xf bank_mask:0xf
	s_nop 0
	v_mov_b32_e32 v69, v67
	v_mov_b32_e32 v68, v66
	s_nop 0
	v_permlane16_swap_b32_e32 v67, v69
	v_permlane16_swap_b32_e32 v66, v68
	s_nop 0
	v_add_f32_e32 v67, v67, v69
	v_add_f32_e32 v66, v66, v68
	s_nop 0
	v_mov_b32_e32 v69, v67
	v_mov_b32_e32 v68, v66
	s_nop 0
	v_permlane32_swap_b32_e32 v67, v69
	v_permlane32_swap_b32_e32 v66, v68
	s_nop 0
	v_add_f32_e32 v67, v67, v69
	v_add_f32_e32 v66, v66, v68
	s_nop 0
	s_nop 0
	v_pk_fma_f32 v[66:67], v[66:67], s[8:9], v[126:127] op_sel_hi:[1,0,0]
	v_mov_b32_e32 v69, v57
	v_mul_f32_e32 v68, 0x4b800000, v67
	v_cmp_gt_f32_e64 s[0:1], s6, v67
	v_cmp_gt_f32_e32 vcc, s6, v66
	s_nop 0
	v_cndmask_b32_e64 v67, v67, v68, s[0:1]
	v_rsq_f32_e32 v67, v67
	s_nop 0
	v_mul_f32_e32 v68, 0x45800000, v67
	v_cndmask_b32_e64 v80, v67, v68, s[0:1]
	v_mul_f32_e32 v67, 0x4b800000, v66
	v_cndmask_b32_e32 v66, v66, v67, vcc
	v_rsq_f32_e32 v66, v66
	v_mov_b32_e32 v68, v61
	v_pk_mul_f32 v[68:69], v[68:69], v[68:69]
	v_mul_f32_e32 v67, 0x45800000, v66
	v_cndmask_b32_e32 v78, v66, v67, vcc
	v_mov_b32_e32 v66, v60
	v_mov_b32_e32 v67, v56
	v_pk_fma_f32 v[66:67], v[66:67], v[66:67], v[68:69]
	v_mov_b32_e32 v68, v62
	v_mov_b32_e32 v69, v58
	v_pk_fma_f32 v[66:67], v[68:69], v[68:69], v[66:67]
	v_mov_b32_e32 v68, v63
	v_mov_b32_e32 v69, v59
	v_pk_fma_f32 v[66:67], v[68:69], v[68:69], v[66:67]
	v_mov_b32_e32 v68, v40
	v_mov_b32_e32 v69, v24
	v_pk_fma_f32 v[68:69], v[68:69], v[68:69], v[70:71]
	v_mov_b32_e32 v70, v42
	v_mov_b32_e32 v71, v26
	v_pk_fma_f32 v[68:69], v[70:71], v[70:71], v[68:69]
	v_mov_b32_e32 v70, v43
	v_mov_b32_e32 v71, v27
	v_pk_fma_f32 v[68:69], v[70:71], v[70:71], v[68:69]
	v_mov_b32_e32 v70, v52
	v_mov_b32_e32 v71, v48
	v_pk_fma_f32 v[70:71], v[70:71], v[70:71], v[72:73]
	v_mov_b32_e32 v72, v54
	v_mov_b32_e32 v73, v50
	v_pk_fma_f32 v[70:71], v[72:73], v[72:73], v[70:71]
	v_mov_b32_e32 v72, v55
	v_mov_b32_e32 v73, v51
	v_pk_fma_f32 v[70:71], v[72:73], v[72:73], v[70:71]
	v_mov_b32_e32 v72, v44
	v_mov_b32_e32 v73, v28
	v_pk_fma_f32 v[72:73], v[72:73], v[72:73], v[74:75]
	v_mov_b32_e32 v74, v46
	v_mov_b32_e32 v75, v30
	v_pk_fma_f32 v[72:73], v[74:75], v[74:75], v[72:73]
	v_mov_b32_e32 v74, v47
	v_mov_b32_e32 v75, v31
	v_pk_fma_f32 v[72:73], v[74:75], v[74:75], v[72:73]
	v_mov_b32_e32 v74, v70
	v_mov_b32_e32 v75, v66
	v_mov_b32_e32 v66, v71
	v_pk_add_f32 v[66:67], v[74:75], v[66:67]
	v_mov_b32_e32 v70, v72
	v_mov_b32_e32 v71, v68
	v_pk_add_f32 v[66:67], v[66:67], v[70:71]
	v_mov_b32_e32 v68, v73
	v_pk_add_f32 v[66:67], v[66:67], v[68:69]
	v_lshl_add_u64 v[70:71], v[76:77], 0, v[106:107]
	s_nop 0
	s_nop 1
	v_add_f32_dpp v67, v67, v67 quad_perm:[1,0,3,2] row_mask:0xf bank_mask:0xf
	v_add_f32_dpp v66, v66, v66 quad_perm:[1,0,3,2] row_mask:0xf bank_mask:0xf
	s_nop 0
	v_add_f32_dpp v67, v67, v67 quad_perm:[2,3,0,1] row_mask:0xf bank_mask:0xf
	v_add_f32_dpp v66, v66, v66 quad_perm:[2,3,0,1] row_mask:0xf bank_mask:0xf
	s_nop 0
	v_add_f32_dpp v67, v67, v67 row_half_mirror row_mask:0xf bank_mask:0xf
	v_add_f32_dpp v66, v66, v66 row_half_mirror row_mask:0xf bank_mask:0xf
	s_nop 0
	v_add_f32_dpp v67, v67, v67 row_mirror row_mask:0xf bank_mask:0xf
	v_add_f32_dpp v66, v66, v66 row_mirror row_mask:0xf bank_mask:0xf
	s_nop 0
	v_mov_b32_e32 v69, v67
	v_mov_b32_e32 v68, v66
	s_nop 0
	v_permlane16_swap_b32_e32 v67, v69
	v_permlane16_swap_b32_e32 v66, v68
	s_nop 0
	v_add_f32_e32 v67, v67, v69
	v_add_f32_e32 v66, v66, v68
	s_nop 0
	v_mov_b32_e32 v69, v67
	v_mov_b32_e32 v68, v66
	s_nop 0
	v_permlane32_swap_b32_e32 v67, v69
	v_permlane32_swap_b32_e32 v66, v68
	s_nop 0
	v_add_f32_e32 v67, v67, v69
	v_add_f32_e32 v66, v66, v68
	s_nop 0
	s_nop 0
	v_pk_fma_f32 v[66:67], v[66:67], s[8:9], v[126:127] op_sel_hi:[1,0,0]
	s_nop 0
	v_mul_f32_e32 v68, 0x4b800000, v67
	v_cmp_gt_f32_e64 s[0:1], s6, v67
	v_cmp_gt_f32_e32 vcc, s6, v66
	s_nop 0
	v_cndmask_b32_e64 v67, v67, v68, s[0:1]
	v_rsq_f32_e32 v67, v67
	s_nop 0
	v_mul_f32_e32 v68, 0x45800000, v67
	v_cndmask_b32_e64 v84, v67, v68, s[0:1]
	v_mul_f32_e32 v67, 0x4b800000, v66
	v_cndmask_b32_e32 v66, v66, v67, vcc
	v_rsq_f32_e32 v66, v66
	s_mov_b64 s[0:1], 0x4000
	v_lshl_add_u64 v[88:89], v[64:65], 0, s[0:1]
	v_lshl_add_u64 v[68:69], v[88:89], 0, v[106:107]
	v_mul_f32_e32 v67, 0x45800000, v66
	v_cndmask_b32_e32 v82, v66, v67, vcc
	global_load_dwordx4 v[64:67], v[100:101], off
	global_load_dwordx4 v[72:75], v[68:69], off
	s_nop 0
	global_load_dwordx4 v[68:71], v[70:71], off
	v_readlane_b32 s0, v255, 7
	s_waitcnt vmcnt(2)
	v_mov_b32_e32 v93, v66
	s_waitcnt vmcnt(1)
	v_mov_b32_e32 v91, v74
	v_mov_b32_e32 v74, v73
	v_mov_b32_e32 v90, v72
	v_pk_add_f32 v[72:73], v[74:75], 1.0 op_sel_hi:[1,0]
	v_mov_b32_e32 v75, v34
	v_mov_b32_e32 v34, v33
	v_mov_b32_e32 v74, v32
	v_pk_mul_f32 v[32:33], v[34:35], v[80:81] op_sel_hi:[1,0]
	v_mov_b32_e32 v66, v65
	v_pk_mul_f32 v[74:75], v[74:75], v[80:81] op_sel_hi:[1,0]
	v_mov_b32_e32 v92, v64
	s_waitcnt vmcnt(0)
	v_mov_b32_e32 v95, v70
	v_pk_mul_f32 v[32:33], v[32:33], v[66:67]
	v_mov_b32_e32 v70, v69
	v_pk_add_f32 v[90:91], v[90:91], 1.0 op_sel_hi:[1,0]
	v_pk_mul_f32 v[74:75], v[74:75], v[92:93]
	v_mov_b32_e32 v94, v68
	v_pk_fma_f32 v[32:33], v[32:33], v[72:73], v[70:71]
	v_pk_fma_f32 v[74:75], v[74:75], v[90:91], v[94:95]
	v_cvt_pk_bf16_f32 v33, v75, v33
	v_cvt_pk_bf16_f32 v32, v74, v32
	v_mov_b32_e32 v34, v36
	v_mov_b32_e32 v35, v38
	v_pk_mul_f32 v[34:35], v[34:35], v[78:79] op_sel_hi:[1,0]
	v_mov_b32_e32 v38, v37
	v_pk_mul_f32 v[34:35], v[34:35], v[92:93]
	v_pk_mul_f32 v[36:37], v[38:39], v[78:79] op_sel_hi:[1,0]
	v_pk_fma_f32 v[34:35], v[34:35], v[90:91], v[94:95]
	v_pk_mul_f32 v[36:37], v[36:37], v[66:67]
	v_and_b32_sdwa v38, v35, v218 dst_sel:DWORD dst_unused:UNUSED_PAD src0_sel:WORD_1 src1_sel:DWORD
	v_pk_fma_f32 v[36:37], v[36:37], v[72:73], v[70:71]
	v_cvt_pk_bf16_f32 v34, v34, v36
	v_add3_u32 v35, v35, v38, s80
	v_and_b32_sdwa v38, v37, v218 dst_sel:DWORD dst_unused:UNUSED_PAD src0_sel:WORD_1 src1_sel:DWORD
	v_add3_u32 v37, v37, v38, s80
	v_and_b32_e32 v37, 0xffff0000, v37
	v_or_b32_sdwa v35, v37, v35 dst_sel:DWORD dst_unused:UNUSED_PAD src0_sel:DWORD src1_sel:WORD_1
	v_mov_b32_e32 v36, v60
	v_mov_b32_e32 v37, v62
	v_pk_mul_f32 v[36:37], v[36:37], v[84:85] op_sel_hi:[1,0]
	v_mov_b32_e32 v62, v61
	v_pk_mul_f32 v[36:37], v[92:93], v[36:37]
	v_pk_mul_f32 v[38:39], v[62:63], v[84:85] op_sel_hi:[1,0]
	v_pk_fma_f32 v[36:37], v[36:37], v[90:91], v[94:95]
	v_pk_mul_f32 v[38:39], v[66:67], v[38:39]
	v_and_b32_sdwa v60, v37, v218 dst_sel:DWORD dst_unused:UNUSED_PAD src0_sel:WORD_1 src1_sel:DWORD
	v_pk_fma_f32 v[38:39], v[38:39], v[72:73], v[70:71]
	v_cvt_pk_bf16_f32 v36, v36, v38
	v_add3_u32 v37, v37, v60, s80
	v_and_b32_sdwa v60, v39, v218 dst_sel:DWORD dst_unused:UNUSED_PAD src0_sel:WORD_1 src1_sel:DWORD
	v_add3_u32 v39, v39, v60, s80
	v_and_b32_e32 v39, 0xffff0000, v39
	v_or_b32_sdwa v37, v39, v37 dst_sel:DWORD dst_unused:UNUSED_PAD src0_sel:DWORD src1_sel:WORD_1
	v_mov_b32_e32 v38, v52
	v_mov_b32_e32 v39, v54
	v_pk_mul_f32 v[38:39], v[38:39], v[82:83] op_sel_hi:[1,0]
	v_mov_b32_e32 v54, v53
	v_pk_mul_f32 v[38:39], v[92:93], v[38:39]
	v_pk_mul_f32 v[52:53], v[54:55], v[82:83] op_sel_hi:[1,0]
	v_pk_fma_f32 v[38:39], v[90:91], v[38:39], v[94:95]
	v_pk_mul_f32 v[52:53], v[66:67], v[52:53]
	v_and_b32_sdwa v54, v39, v218 dst_sel:DWORD dst_unused:UNUSED_PAD src0_sel:WORD_1 src1_sel:DWORD
	v_pk_fma_f32 v[52:53], v[72:73], v[52:53], v[70:71]
	v_cvt_pk_bf16_f32 v38, v38, v52
	v_add3_u32 v39, v39, v54, s80
	v_and_b32_sdwa v54, v53, v218 dst_sel:DWORD dst_unused:UNUSED_PAD src0_sel:WORD_1 src1_sel:DWORD
	global_store_dwordx2 v[86:87], v[32:33], off
	v_lshl_add_u64 v[32:33], v[102:103], 0, v[118:119]
	v_add3_u32 v53, v53, v54, s80
	global_store_dwordx2 v[32:33], v[34:35], off
	v_lshl_add_u64 v[34:35], v[102:103], 0, v[116:117]
	v_and_b32_e32 v53, 0xffff0000, v53
	global_store_dwordx2 v[34:35], v[36:37], off
	v_lshl_add_u64 v[36:37], v[102:103], 0, v[114:115]
	v_or_b32_sdwa v39, v53, v39 dst_sel:DWORD dst_unused:UNUSED_PAD src0_sel:DWORD src1_sel:WORD_1
	global_store_dwordx2 v[36:37], v[38:39], off
	v_lshl_add_u64 v[64:65], v[76:77], 0, v[108:109]
	v_lshl_add_u64 v[38:39], v[88:89], 0, v[108:109]
	global_load_dwordx4 v[52:55], v[100:101], off offset:1024
	global_load_dwordx4 v[60:63], v[38:39], off
	s_nop 0
	global_load_dwordx4 v[64:67], v[64:65], off
	v_add_u32_e32 v104, s0, v104
	s_waitcnt vmcnt(2)
	v_mov_b32_e32 v69, v54
	s_waitcnt vmcnt(1)
	v_mov_b32_e32 v39, v62
	v_mov_b32_e32 v62, v61
	v_mov_b32_e32 v38, v60
	v_pk_add_f32 v[60:61], v[62:63], 1.0 op_sel_hi:[1,0]
	v_mov_b32_e32 v63, v18
	v_mov_b32_e32 v18, v17
	v_mov_b32_e32 v62, v16
	v_pk_mul_f32 v[16:17], v[18:19], v[80:81] op_sel_hi:[1,0]
	v_mov_b32_e32 v54, v53
	v_pk_mul_f32 v[62:63], v[62:63], v[80:81] op_sel_hi:[1,0]
	v_mov_b32_e32 v68, v52
	s_waitcnt vmcnt(0)
	v_mov_b32_e32 v71, v66
	v_pk_mul_f32 v[16:17], v[16:17], v[54:55]
	v_mov_b32_e32 v66, v65
	v_pk_add_f32 v[38:39], v[38:39], 1.0 op_sel_hi:[1,0]
	v_pk_mul_f32 v[62:63], v[62:63], v[68:69]
	v_mov_b32_e32 v70, v64
	v_pk_fma_f32 v[16:17], v[16:17], v[60:61], v[66:67]
	v_pk_fma_f32 v[62:63], v[62:63], v[38:39], v[70:71]
	v_cvt_pk_bf16_f32 v17, v63, v17
	v_cvt_pk_bf16_f32 v16, v62, v16
	global_store_dwordx2 v[86:87], v[16:17], off offset:512
	v_mov_b32_e32 v16, v20
	v_mov_b32_e32 v17, v22
	v_pk_mul_f32 v[16:17], v[16:17], v[78:79] op_sel_hi:[1,0]
	v_mov_b32_e32 v22, v21
	v_pk_mul_f32 v[16:17], v[16:17], v[68:69]
	v_pk_mul_f32 v[18:19], v[22:23], v[78:79] op_sel_hi:[1,0]
	v_pk_fma_f32 v[16:17], v[16:17], v[38:39], v[70:71]
	v_pk_mul_f32 v[18:19], v[18:19], v[54:55]
	v_and_b32_sdwa v20, v17, v218 dst_sel:DWORD dst_unused:UNUSED_PAD src0_sel:WORD_1 src1_sel:DWORD
	v_pk_fma_f32 v[18:19], v[18:19], v[60:61], v[66:67]
	v_cvt_pk_bf16_f32 v16, v16, v18
	v_add3_u32 v17, v17, v20, s80
	v_and_b32_sdwa v20, v19, v218 dst_sel:DWORD dst_unused:UNUSED_PAD src0_sel:WORD_1 src1_sel:DWORD
	v_add3_u32 v19, v19, v20, s80
	v_and_b32_e32 v19, 0xffff0000, v19
	v_or_b32_sdwa v17, v19, v17 dst_sel:DWORD dst_unused:UNUSED_PAD src0_sel:DWORD src1_sel:WORD_1
	global_store_dwordx2 v[32:33], v[16:17], off offset:512
	v_mov_b32_e32 v16, v56
	v_mov_b32_e32 v17, v58
	v_pk_mul_f32 v[16:17], v[16:17], v[84:85] op_sel_hi:[1,0]
	v_mov_b32_e32 v58, v57
	v_pk_mul_f32 v[16:17], v[16:17], v[68:69]
	v_pk_mul_f32 v[18:19], v[58:59], v[84:85] op_sel_hi:[1,0]
	v_pk_fma_f32 v[16:17], v[16:17], v[38:39], v[70:71]
	v_pk_mul_f32 v[18:19], v[18:19], v[54:55]
	v_and_b32_sdwa v20, v17, v218 dst_sel:DWORD dst_unused:UNUSED_PAD src0_sel:WORD_1 src1_sel:DWORD
	v_pk_fma_f32 v[18:19], v[18:19], v[60:61], v[66:67]
	v_cvt_pk_bf16_f32 v16, v16, v18
	v_add3_u32 v17, v17, v20, s80
	v_and_b32_sdwa v20, v19, v218 dst_sel:DWORD dst_unused:UNUSED_PAD src0_sel:WORD_1 src1_sel:DWORD
	v_add3_u32 v19, v19, v20, s80
	v_and_b32_e32 v19, 0xffff0000, v19
	v_or_b32_sdwa v17, v19, v17 dst_sel:DWORD dst_unused:UNUSED_PAD src0_sel:DWORD src1_sel:WORD_1
	global_store_dwordx2 v[34:35], v[16:17], off offset:512
	v_mov_b32_e32 v16, v48
	v_mov_b32_e32 v17, v50
	v_pk_mul_f32 v[16:17], v[16:17], v[82:83] op_sel_hi:[1,0]
	v_mov_b32_e32 v50, v49
	v_pk_mul_f32 v[16:17], v[16:17], v[68:69]
	v_pk_mul_f32 v[18:19], v[50:51], v[82:83] op_sel_hi:[1,0]
	v_pk_fma_f32 v[16:17], v[16:17], v[38:39], v[70:71]
	v_pk_mul_f32 v[18:19], v[18:19], v[54:55]
	v_and_b32_sdwa v20, v17, v218 dst_sel:DWORD dst_unused:UNUSED_PAD src0_sel:WORD_1 src1_sel:DWORD
	v_pk_fma_f32 v[18:19], v[18:19], v[60:61], v[66:67]
	v_cvt_pk_bf16_f32 v16, v16, v18
	v_add3_u32 v17, v17, v20, s80
	v_and_b32_sdwa v20, v19, v218 dst_sel:DWORD dst_unused:UNUSED_PAD src0_sel:WORD_1 src1_sel:DWORD
	v_add3_u32 v19, v19, v20, s80
	v_and_b32_e32 v19, 0xffff0000, v19
	v_or_b32_sdwa v17, v19, v17 dst_sel:DWORD dst_unused:UNUSED_PAD src0_sel:DWORD src1_sel:WORD_1
	global_store_dwordx2 v[36:37], v[16:17], off offset:512
	v_lshl_add_u64 v[20:21], v[88:89], 0, v[110:111]
	v_lshl_add_u64 v[38:39], v[76:77], 0, v[110:111]
	global_load_dwordx4 v[16:19], v[100:101], off offset:2048
	s_nop 0
	global_load_dwordx4 v[20:23], v[20:21], off
	s_nop 0
	global_load_dwordx4 v[48:51], v[38:39], off
	s_waitcnt vmcnt(2)
	v_mov_b32_e32 v53, v18
	s_waitcnt vmcnt(1)
	v_mov_b32_e32 v39, v22
	v_mov_b32_e32 v22, v21
	v_mov_b32_e32 v38, v20
	v_pk_add_f32 v[20:21], v[22:23], 1.0 op_sel_hi:[1,0]
	v_mov_b32_e32 v23, v10
	v_mov_b32_e32 v10, v9
	v_mov_b32_e32 v22, v8
	v_pk_mul_f32 v[8:9], v[10:11], v[80:81] op_sel_hi:[1,0]
	v_mov_b32_e32 v18, v17
	v_pk_mul_f32 v[22:23], v[22:23], v[80:81] op_sel_hi:[1,0]
	v_mov_b32_e32 v52, v16
	s_waitcnt vmcnt(0)
	v_mov_b32_e32 v55, v50
	v_pk_mul_f32 v[8:9], v[8:9], v[18:19]
	v_mov_b32_e32 v50, v49
	v_pk_add_f32 v[38:39], v[38:39], 1.0 op_sel_hi:[1,0]
	v_pk_mul_f32 v[22:23], v[22:23], v[52:53]
	v_mov_b32_e32 v54, v48
	v_pk_fma_f32 v[8:9], v[8:9], v[20:21], v[50:51]
	v_pk_fma_f32 v[22:23], v[22:23], v[38:39], v[54:55]
	v_cvt_pk_bf16_f32 v9, v23, v9
	v_cvt_pk_bf16_f32 v8, v22, v8
	global_store_dwordx2 v[86:87], v[8:9], off offset:1024
	v_mov_b32_e32 v8, v12
	v_mov_b32_e32 v9, v14
	v_pk_mul_f32 v[8:9], v[8:9], v[78:79] op_sel_hi:[1,0]
	v_mov_b32_e32 v14, v13
	v_pk_mul_f32 v[8:9], v[8:9], v[52:53]
	v_pk_mul_f32 v[10:11], v[14:15], v[78:79] op_sel_hi:[1,0]
	v_pk_fma_f32 v[8:9], v[8:9], v[38:39], v[54:55]
	v_pk_mul_f32 v[10:11], v[10:11], v[18:19]
	v_and_b32_sdwa v12, v9, v218 dst_sel:DWORD dst_unused:UNUSED_PAD src0_sel:WORD_1 src1_sel:DWORD
	v_pk_fma_f32 v[10:11], v[10:11], v[20:21], v[50:51]
	v_cvt_pk_bf16_f32 v8, v8, v10
	v_add3_u32 v9, v9, v12, s80
	v_and_b32_sdwa v12, v11, v218 dst_sel:DWORD dst_unused:UNUSED_PAD src0_sel:WORD_1 src1_sel:DWORD
	v_add3_u32 v11, v11, v12, s80
	v_and_b32_e32 v11, 0xffff0000, v11
	v_or_b32_sdwa v9, v11, v9 dst_sel:DWORD dst_unused:UNUSED_PAD src0_sel:DWORD src1_sel:WORD_1
	global_store_dwordx2 v[32:33], v[8:9], off offset:1024
	v_mov_b32_e32 v8, v40
	v_mov_b32_e32 v9, v42
	v_pk_mul_f32 v[8:9], v[8:9], v[84:85] op_sel_hi:[1,0]
	v_mov_b32_e32 v42, v41
	v_pk_mul_f32 v[8:9], v[8:9], v[52:53]
	v_pk_mul_f32 v[10:11], v[42:43], v[84:85] op_sel_hi:[1,0]
	v_pk_fma_f32 v[8:9], v[8:9], v[38:39], v[54:55]
	v_pk_mul_f32 v[10:11], v[10:11], v[18:19]
	v_and_b32_sdwa v12, v9, v218 dst_sel:DWORD dst_unused:UNUSED_PAD src0_sel:WORD_1 src1_sel:DWORD
	v_pk_fma_f32 v[10:11], v[10:11], v[20:21], v[50:51]
	v_cvt_pk_bf16_f32 v8, v8, v10
	v_add3_u32 v9, v9, v12, s80
	v_and_b32_sdwa v12, v11, v218 dst_sel:DWORD dst_unused:UNUSED_PAD src0_sel:WORD_1 src1_sel:DWORD
	v_add3_u32 v11, v11, v12, s80
	v_and_b32_e32 v11, 0xffff0000, v11
	v_or_b32_sdwa v9, v11, v9 dst_sel:DWORD dst_unused:UNUSED_PAD src0_sel:DWORD src1_sel:WORD_1
	global_store_dwordx2 v[34:35], v[8:9], off offset:1024
	v_mov_b32_e32 v8, v44
	v_mov_b32_e32 v9, v46
	v_pk_mul_f32 v[8:9], v[8:9], v[82:83] op_sel_hi:[1,0]
	v_mov_b32_e32 v46, v45
	v_pk_mul_f32 v[8:9], v[8:9], v[52:53]
	v_pk_mul_f32 v[10:11], v[46:47], v[82:83] op_sel_hi:[1,0]
	v_pk_fma_f32 v[8:9], v[8:9], v[38:39], v[54:55]
	v_pk_mul_f32 v[10:11], v[10:11], v[18:19]
	v_and_b32_sdwa v12, v9, v218 dst_sel:DWORD dst_unused:UNUSED_PAD src0_sel:WORD_1 src1_sel:DWORD
	v_pk_fma_f32 v[10:11], v[10:11], v[20:21], v[50:51]
	v_cvt_pk_bf16_f32 v8, v8, v10
	v_add3_u32 v9, v9, v12, s80
	v_and_b32_sdwa v12, v11, v218 dst_sel:DWORD dst_unused:UNUSED_PAD src0_sel:WORD_1 src1_sel:DWORD
	v_add3_u32 v11, v11, v12, s80
	v_and_b32_e32 v11, 0xffff0000, v11
	v_or_b32_sdwa v9, v11, v9 dst_sel:DWORD dst_unused:UNUSED_PAD src0_sel:DWORD src1_sel:WORD_1
	global_store_dwordx2 v[36:37], v[8:9], off offset:1024
	v_lshl_add_u64 v[12:13], v[88:89], 0, v[112:113]
	v_lshl_add_u64 v[16:17], v[76:77], 0, v[112:113]
	global_load_dwordx4 v[8:11], v[100:101], off offset:3072
	s_nop 0
	global_load_dwordx4 v[12:15], v[12:13], off
	s_nop 0
	global_load_dwordx4 v[16:19], v[16:17], off
	s_waitcnt vmcnt(2)
	v_mov_b32_e32 v23, v10
	s_waitcnt vmcnt(1)
	v_mov_b32_e32 v21, v14
	v_mov_b32_e32 v14, v13
	v_mov_b32_e32 v20, v12
	v_pk_add_f32 v[12:13], v[14:15], 1.0 op_sel_hi:[1,0]
	v_mov_b32_e32 v15, v2
	v_mov_b32_e32 v2, v1
	v_mov_b32_e32 v14, v0
	v_pk_mul_f32 v[0:1], v[2:3], v[80:81] op_sel_hi:[1,0]
	v_mov_b32_e32 v10, v9
	v_pk_mul_f32 v[14:15], v[14:15], v[80:81] op_sel_hi:[1,0]
	v_mov_b32_e32 v22, v8
	s_waitcnt vmcnt(0)
	v_mov_b32_e32 v39, v18
	v_pk_mul_f32 v[0:1], v[0:1], v[10:11]
	v_mov_b32_e32 v18, v17
	v_pk_add_f32 v[20:21], v[20:21], 1.0 op_sel_hi:[1,0]
	v_pk_mul_f32 v[14:15], v[14:15], v[22:23]
	v_mov_b32_e32 v38, v16
	v_pk_fma_f32 v[0:1], v[0:1], v[12:13], v[18:19]
	v_pk_fma_f32 v[14:15], v[14:15], v[20:21], v[38:39]
	v_cvt_pk_bf16_f32 v1, v15, v1
	v_cvt_pk_bf16_f32 v0, v14, v0
	global_store_dwordx2 v[86:87], v[0:1], off offset:1536
	v_mov_b32_e32 v0, v4
	v_mov_b32_e32 v1, v6
	v_pk_mul_f32 v[0:1], v[0:1], v[78:79] op_sel_hi:[1,0]
	v_mov_b32_e32 v6, v5
	v_pk_mul_f32 v[0:1], v[0:1], v[22:23]
	v_pk_mul_f32 v[2:3], v[6:7], v[78:79] op_sel_hi:[1,0]
	v_pk_fma_f32 v[0:1], v[0:1], v[20:21], v[38:39]
	v_pk_mul_f32 v[2:3], v[2:3], v[10:11]
	v_and_b32_sdwa v4, v1, v218 dst_sel:DWORD dst_unused:UNUSED_PAD src0_sel:WORD_1 src1_sel:DWORD
	v_pk_fma_f32 v[2:3], v[2:3], v[12:13], v[18:19]
	v_cvt_pk_bf16_f32 v0, v0, v2
	v_add3_u32 v1, v1, v4, s80
	v_and_b32_sdwa v4, v3, v218 dst_sel:DWORD dst_unused:UNUSED_PAD src0_sel:WORD_1 src1_sel:DWORD
	v_add3_u32 v3, v3, v4, s80
	v_and_b32_e32 v3, 0xffff0000, v3
	v_or_b32_sdwa v1, v3, v1 dst_sel:DWORD dst_unused:UNUSED_PAD src0_sel:DWORD src1_sel:WORD_1
	global_store_dwordx2 v[32:33], v[0:1], off offset:1536
	v_mov_b32_e32 v0, v24
	v_mov_b32_e32 v1, v26
	v_pk_mul_f32 v[0:1], v[0:1], v[84:85] op_sel_hi:[1,0]
	v_mov_b32_e32 v26, v25
	v_pk_mul_f32 v[0:1], v[0:1], v[22:23]
	v_pk_mul_f32 v[2:3], v[26:27], v[84:85] op_sel_hi:[1,0]
	v_pk_fma_f32 v[0:1], v[0:1], v[20:21], v[38:39]
	v_pk_mul_f32 v[2:3], v[2:3], v[10:11]
	v_and_b32_sdwa v4, v1, v218 dst_sel:DWORD dst_unused:UNUSED_PAD src0_sel:WORD_1 src1_sel:DWORD
	v_pk_fma_f32 v[2:3], v[2:3], v[12:13], v[18:19]
	v_cvt_pk_bf16_f32 v0, v0, v2
	v_add3_u32 v1, v1, v4, s80
	v_and_b32_sdwa v4, v3, v218 dst_sel:DWORD dst_unused:UNUSED_PAD src0_sel:WORD_1 src1_sel:DWORD
	v_add3_u32 v3, v3, v4, s80
	v_and_b32_e32 v3, 0xffff0000, v3
	v_or_b32_sdwa v1, v3, v1 dst_sel:DWORD dst_unused:UNUSED_PAD src0_sel:DWORD src1_sel:WORD_1
	global_store_dwordx2 v[34:35], v[0:1], off offset:1536
	v_mov_b32_e32 v0, v28
	v_mov_b32_e32 v1, v30
	v_pk_mul_f32 v[0:1], v[0:1], v[82:83] op_sel_hi:[1,0]
	v_mov_b32_e32 v30, v29
	v_pk_mul_f32 v[0:1], v[0:1], v[22:23]
	v_pk_mul_f32 v[2:3], v[30:31], v[82:83] op_sel_hi:[1,0]
	v_pk_fma_f32 v[0:1], v[0:1], v[20:21], v[38:39]
	v_pk_mul_f32 v[2:3], v[2:3], v[10:11]
	v_and_b32_sdwa v4, v1, v218 dst_sel:DWORD dst_unused:UNUSED_PAD src0_sel:WORD_1 src1_sel:DWORD
	v_pk_fma_f32 v[2:3], v[2:3], v[12:13], v[18:19]
	v_cvt_pk_bf16_f32 v0, v0, v2
	v_add3_u32 v1, v1, v4, s80
	v_and_b32_sdwa v4, v3, v218 dst_sel:DWORD dst_unused:UNUSED_PAD src0_sel:WORD_1 src1_sel:DWORD
	v_add3_u32 v3, v3, v4, s80
	v_and_b32_e32 v3, 0xffff0000, v3
	v_or_b32_sdwa v1, v3, v1 dst_sel:DWORD dst_unused:UNUSED_PAD src0_sel:DWORD src1_sel:WORD_1
	global_store_dwordx2 v[36:37], v[0:1], off offset:1536
	s_cbranch_scc1 .LBB0_179

.LBB0_182:
	v_min_i32_e32 v2, 0x4000, v16
	v_ashrrev_i32_e32 v2, 13, v2
	v_mov_b32_e32 v53, v193
	v_lshlrev_b64 v[60:61], 11, v[16:17]
	v_add_u32_e32 v2, s8, v2
	v_lshl_add_u64 v[0:1], v[0:1], 0, v[52:53]
	v_lshl_add_u64 v[16:17], v[44:45], 0, v[60:61]
	v_mul_hi_i32_i24_e32 v63, 0x6000, v2
	v_mul_i32_i24_e32 v62, 0x6000, v2
	global_load_dwordx4 v[12:15], v[0:1], off nt
	global_load_dwordx4 v[8:11], v[0:1], off offset:1024 nt
	global_load_dwordx4 v[4:7], v[0:1], off offset:2048 nt
	s_nop 0
	global_load_dwordx4 v[0:3], v[0:1], off offset:3072 nt
	s_nop 0
	global_load_dwordx2 v[24:25], v[16:17], off
	global_load_dwordx2 v[32:33], v[16:17], off offset:512
	global_load_dwordx2 v[40:41], v[16:17], off offset:1024
	global_load_dwordx2 v[76:77], v[16:17], off offset:1536
	v_lshl_add_u64 v[18:19], s[90:91], 0, v[62:63]
	v_lshl_add_u64 v[20:21], v[18:19], 0, v[52:53]
	s_mov_b64 s[0:1], 0x345a000
	v_lshl_add_u64 v[84:85], v[20:21], 0, s[0:1]
	s_mov_b32 s0, 0x345a000
	v_add_co_u32_e32 v20, vcc, s0, v20
	global_load_dwordx4 v[16:19], v[46:47], off
	s_nop 0
	v_addc_co_u32_e32 v21, vcc, 0, v21, vcc
	global_load_dwordx4 v[20:23], v[20:21], off
	s_mov_b32 s0, 0x800000
	s_mov_b64 s[10:11], 0x3000
	v_mov_b32_e32 v59, v193
	s_waitcnt vmcnt(5)
	v_and_b32_e32 v67, 0xffff0000, v24
	s_waitcnt vmcnt(4)
	v_and_b32_e32 v69, 0xffff0000, v32
	v_lshlrev_b32_e32 v66, 16, v24
	v_lshlrev_b32_e32 v68, 16, v32
	v_mov_b32_e32 v34, v67
	v_mov_b32_e32 v35, v69
	v_lshlrev_b32_e32 v70, 16, v25
	v_and_b32_e32 v73, 0xffff0000, v33
	v_lshlrev_b32_e32 v72, 16, v33
	v_mov_b32_e32 v32, v66
	v_mov_b32_e32 v33, v68
	v_pk_mul_f32 v[34:35], v[34:35], v[34:35]
	v_and_b32_e32 v71, 0xffff0000, v25
	global_load_dwordx4 v[28:31], v[46:47], off offset:1024
	global_load_dwordx4 v[24:27], v[84:85], off offset:1024
	v_pk_fma_f32 v[32:33], v[32:33], v[32:33], v[34:35]
	v_mov_b32_e32 v34, v70
	v_mov_b32_e32 v35, v72
	v_mov_b32_e32 v36, v71
	v_mov_b32_e32 v37, v73
	v_pk_fma_f32 v[32:33], v[34:35], v[34:35], v[32:33]
	s_waitcnt vmcnt(5)
	v_and_b32_e32 v75, 0xffff0000, v40
	v_pk_fma_f32 v[78:79], v[36:37], v[36:37], v[32:33]
	global_load_dwordx4 v[36:39], v[46:47], off offset:2048
	global_load_dwordx4 v[32:35], v[84:85], off offset:2048
	v_lshlrev_b32_e32 v74, 16, v40
	v_and_b32_e32 v83, 0xffff0000, v41
	v_lshlrev_b32_e32 v82, 16, v41
	global_load_dwordx4 v[40:43], v[46:47], off offset:3072
	global_load_dwordx4 v[92:95], v[84:85], off offset:3072
	s_waitcnt vmcnt(8)
	v_and_b32_e32 v81, 0xffff0000, v76
	v_lshlrev_b32_e32 v80, 16, v76
	v_mov_b32_e32 v96, v75
	v_mov_b32_e32 v97, v81
	v_and_b32_e32 v85, 0xffff0000, v77
	v_lshlrev_b32_e32 v84, 16, v77
	v_mov_b32_e32 v76, v74
	v_mov_b32_e32 v77, v80
	v_pk_mul_f32 v[96:97], v[96:97], v[96:97]
	v_mov_b32_e32 v98, v83
	v_pk_fma_f32 v[76:77], v[76:77], v[76:77], v[96:97]
	v_mov_b32_e32 v96, v82
	v_mov_b32_e32 v97, v84
	v_mov_b32_e32 v99, v85
	v_pk_fma_f32 v[76:77], v[96:97], v[96:97], v[76:77]
	v_add_f32_e32 v55, v78, v79
	v_pk_fma_f32 v[76:77], v[98:99], v[98:99], v[76:77]
	s_nop 0
	v_add_f32_e32 v55, v55, v76
	v_add_f32_e32 v55, v55, v77
	s_nop 0
	s_nop 1
	v_add_f32_dpp v55, v55, v55 quad_perm:[1,0,3,2] row_mask:0xf bank_mask:0xf
	s_nop 1
	v_add_f32_dpp v55, v55, v55 quad_perm:[2,3,0,1] row_mask:0xf bank_mask:0xf
	s_nop 1
	v_add_f32_dpp v55, v55, v55 row_half_mirror row_mask:0xf bank_mask:0xf
	s_nop 1
	v_add_f32_dpp v55, v55, v55 row_mirror row_mask:0xf bank_mask:0xf
	s_nop 1
	v_mov_b32_e32 v57, v55
	s_nop 1
	v_permlane16_swap_b32_e32 v55, v57
	s_nop 1
	v_add_f32_e32 v55, v55, v57
	s_nop 1
	v_mov_b32_e32 v57, v55
	s_nop 1
	v_permlane32_swap_b32_e32 v55, v57
	s_nop 1
	v_add_f32_e32 v55, v55, v57
	s_nop 1
	v_fmamk_f32 v55, v55, 0x3a800000, v219
	v_cmp_gt_f32_e32 vcc, s0, v55
	v_mul_f32_e32 v57, 0x4b800000, v55
	s_nop 0
	v_cndmask_b32_e32 v55, v55, v57, vcc
	v_rsq_f32_e32 v55, v55
	s_nop 0
	v_mul_f32_e32 v57, 0x45800000, v55
	v_cndmask_b32_e32 v76, v55, v57, vcc
	v_pk_mul_f32 v[66:67], v[76:77], v[66:67] op_sel_hi:[0,1]
	s_waitcnt vmcnt(7)
	v_pk_mul_f32 v[16:17], v[16:17], v[66:67]
	v_pk_mul_f32 v[66:67], v[76:77], v[70:71] op_sel_hi:[0,1]
	s_waitcnt vmcnt(6)
	v_pk_fma_f32 v[12:13], v[20:21], v[16:17], v[12:13]
	v_pk_mul_f32 v[16:17], v[76:77], v[68:69] op_sel_hi:[0,1]
	v_pk_mul_f32 v[18:19], v[18:19], v[66:67]
	s_waitcnt vmcnt(5)
	v_pk_mul_f32 v[16:17], v[28:29], v[16:17]
	v_pk_fma_f32 v[14:15], v[22:23], v[18:19], v[14:15]
	v_pk_mul_f32 v[18:19], v[76:77], v[72:73] op_sel_hi:[0,1]
	s_waitcnt vmcnt(4)
	v_pk_fma_f32 v[8:9], v[24:25], v[16:17], v[8:9]
	v_pk_mul_f32 v[16:17], v[76:77], v[74:75] op_sel_hi:[0,1]
	v_pk_mul_f32 v[18:19], v[30:31], v[18:19]
	s_waitcnt vmcnt(3)
	v_pk_mul_f32 v[16:17], v[16:17], v[36:37]
	v_pk_fma_f32 v[10:11], v[26:27], v[18:19], v[10:11]
	v_pk_mul_f32 v[18:19], v[76:77], v[82:83] op_sel_hi:[0,1]
	s_waitcnt vmcnt(2)
	v_pk_fma_f32 v[4:5], v[16:17], v[32:33], v[4:5]
	v_pk_mul_f32 v[16:17], v[76:77], v[80:81] op_sel_hi:[0,1]
	v_mov_b32_e32 v22, v13
	v_mov_b32_e32 v23, v9
	v_pk_mul_f32 v[18:19], v[18:19], v[38:39]
	s_waitcnt vmcnt(1)
	v_pk_mul_f32 v[16:17], v[16:17], v[40:41]
	v_mov_b32_e32 v20, v12
	v_mov_b32_e32 v21, v8
	v_pk_mul_f32 v[22:23], v[22:23], v[22:23]
	v_pk_fma_f32 v[6:7], v[18:19], v[34:35], v[6:7]
	v_pk_mul_f32 v[18:19], v[76:77], v[84:85] op_sel_hi:[0,1]
	s_waitcnt vmcnt(0)
	v_pk_fma_f32 v[0:1], v[16:17], v[92:93], v[0:1]
	v_pk_fma_f32 v[20:21], v[20:21], v[20:21], v[22:23]
	v_mov_b32_e32 v22, v14
	v_mov_b32_e32 v23, v10
	v_pk_mul_f32 v[18:19], v[18:19], v[42:43]
	v_pk_fma_f32 v[20:21], v[22:23], v[22:23], v[20:21]
	v_mov_b32_e32 v22, v15
	v_mov_b32_e32 v23, v11
	v_mov_b32_e32 v24, v5
	v_mov_b32_e32 v25, v1
	v_pk_fma_f32 v[2:3], v[18:19], v[94:95], v[2:3]
	v_pk_fma_f32 v[20:21], v[22:23], v[22:23], v[20:21]
	v_mov_b32_e32 v22, v4
	v_mov_b32_e32 v23, v0
	v_pk_mul_f32 v[24:25], v[24:25], v[24:25]
	v_lshl_add_u64 v[16:17], v[64:65], 0, v[52:53]
	v_pk_fma_f32 v[22:23], v[22:23], v[22:23], v[24:25]
	v_mov_b32_e32 v24, v6
	v_mov_b32_e32 v25, v2
	v_pk_fma_f32 v[22:23], v[24:25], v[24:25], v[22:23]
	v_mov_b32_e32 v24, v7
	v_mov_b32_e32 v25, v3
	v_pk_fma_f32 v[22:23], v[24:25], v[24:25], v[22:23]
	v_add_f32_e32 v20, v20, v21
	global_store_dwordx4 v[16:17], v[12:15], off nt
	global_store_dwordx4 v[16:17], v[8:11], off offset:1024 nt
	global_store_dwordx4 v[16:17], v[4:7], off offset:2048 nt
	global_store_dwordx4 v[16:17], v[0:3], off offset:3072 nt
	v_lshl_add_u64 v[16:17], s[96:97], 0, v[62:63]
	v_add_f32_e32 v20, v20, v22
	v_lshl_add_u64 v[18:19], v[16:17], 0, s[10:11]
	v_add_f32_e32 v22, v20, v23
	s_mov_b64 s[10:11], 0x4000
	v_lshl_add_u64 v[20:21], v[16:17], 0, s[10:11]
	ds_bpermute_b32 v16, v86, v22
	v_lshl_add_u64 v[26:27], v[20:21], 0, v[52:53]
	v_lshl_add_u64 v[30:31], v[18:19], 0, v[52:53]
	v_mov_b32_e32 v34, v12
	v_mov_b32_e32 v35, v14
	s_waitcnt lgkmcnt(0)
	v_add_f32_e32 v16, v22, v16
	global_load_dwordx4 v[22:25], v[48:49], off
	s_nop 0
	global_load_dwordx4 v[26:29], v[26:27], off
	s_nop 0
	global_load_dwordx4 v[30:33], v[30:31], off
	ds_bpermute_b32 v17, v87, v16
	v_mov_b32_e32 v14, v13
	v_mov_b32_e32 v55, v193
	v_mov_b32_e32 v57, v193
	s_waitcnt lgkmcnt(0)
	v_add_f32_e32 v16, v16, v17
	ds_bpermute_b32 v17, v88, v16
	s_waitcnt lgkmcnt(0)
	v_add_f32_e32 v16, v16, v17
	ds_bpermute_b32 v17, v89, v16
	s_waitcnt lgkmcnt(0)
	v_add_f32_e32 v16, v16, v17
	ds_bpermute_b32 v17, v90, v16
	s_waitcnt lgkmcnt(0)
	v_add_f32_e32 v16, v16, v17
	ds_bpermute_b32 v17, v91, v16
	s_waitcnt lgkmcnt(0)
	v_add_f32_e32 v16, v16, v17
	v_fmamk_f32 v16, v16, 0x3a800000, v219
	v_cmp_gt_f32_e32 vcc, s0, v16
	v_mul_f32_e32 v17, 0x4b800000, v16
	v_readlane_b32 s0, v255, 11
	v_cndmask_b32_e32 v16, v16, v17, vcc
	v_rsq_f32_e32 v16, v16
	v_add_u32_e32 v192, s0, v192
	s_movk_i32 s0, 0x1ff
	v_readlane_b32 s1, v255, 12
	v_mul_f32_e32 v17, 0x45800000, v16
	v_cndmask_b32_e32 v16, v16, v17, vcc
	v_pk_mul_f32 v[34:35], v[34:35], v[16:17] op_sel_hi:[1,0]
	v_pk_mul_f32 v[12:13], v[14:15], v[16:17] op_sel_hi:[1,0]
	v_cmp_lt_i32_e32 vcc, s0, v192
	s_or_b64 s[6:7], vcc, s[6:7]
	s_waitcnt vmcnt(2)
	v_mov_b32_e32 v36, v22
	v_mov_b32_e32 v37, v24
	v_pk_mul_f32 v[34:35], v[36:37], v[34:35]
	s_waitcnt vmcnt(1)
	v_mov_b32_e32 v36, v26
	v_mov_b32_e32 v37, v28
	v_pk_add_f32 v[36:37], v[36:37], 1.0 op_sel_hi:[1,0]
	s_waitcnt vmcnt(0)
	v_mov_b32_e32 v38, v30
	v_mov_b32_e32 v39, v32
	v_mov_b32_e32 v24, v23
	v_mov_b32_e32 v28, v27
	v_pk_fma_f32 v[34:35], v[36:37], v[34:35], v[38:39]
	v_pk_mul_f32 v[12:13], v[24:25], v[12:13]
	v_pk_add_f32 v[14:15], v[28:29], 1.0 op_sel_hi:[1,0]
	v_mov_b32_e32 v32, v31
	v_pk_fma_f32 v[12:13], v[14:15], v[12:13], v[32:33]
	v_and_b32_sdwa v15, v34, v218 dst_sel:DWORD dst_unused:UNUSED_PAD src0_sel:WORD_1 src1_sel:DWORD
	v_add3_u32 v17, v34, v15, s80
	v_and_b32_sdwa v22, v12, v218 dst_sel:DWORD dst_unused:UNUSED_PAD src0_sel:WORD_1 src1_sel:DWORD
	v_cvt_pk_bf16_f32 v15, v35, v13
	v_add3_u32 v12, v12, v22, s80
	v_and_b32_e32 v12, 0xffff0000, v12
	v_or_b32_sdwa v14, v12, v17 dst_sel:DWORD dst_unused:UNUSED_PAD src0_sel:DWORD src1_sel:WORD_1
	v_lshl_add_u64 v[12:13], v[50:51], 0, v[60:61]
	global_store_dwordx2 v[12:13], v[14:15], off
	v_lshl_add_u64 v[30:31], v[18:19], 0, v[54:55]
	v_lshl_add_u64 v[14:15], v[20:21], 0, v[54:55]
	global_load_dwordx4 v[22:25], v[48:49], off offset:1024
	global_load_dwordx4 v[26:29], v[14:15], off
	s_nop 0
	global_load_dwordx4 v[30:33], v[30:31], off
	v_mov_b32_e32 v14, v8
	v_mov_b32_e32 v15, v10
	v_pk_mul_f32 v[14:15], v[14:15], v[16:17] op_sel_hi:[1,0]
	v_mov_b32_e32 v10, v9
	v_pk_mul_f32 v[8:9], v[10:11], v[16:17] op_sel_hi:[1,0]
	s_waitcnt vmcnt(2)
	v_mov_b32_e32 v34, v22
	v_mov_b32_e32 v35, v24
	v_pk_mul_f32 v[14:15], v[14:15], v[34:35]
	s_waitcnt vmcnt(1)
	v_mov_b32_e32 v34, v26
	v_mov_b32_e32 v35, v28
	v_pk_add_f32 v[34:35], v[34:35], 1.0 op_sel_hi:[1,0]
	s_waitcnt vmcnt(0)
	v_mov_b32_e32 v36, v30
	v_mov_b32_e32 v37, v32
	v_mov_b32_e32 v24, v23
	v_mov_b32_e32 v28, v27
	v_pk_fma_f32 v[14:15], v[14:15], v[34:35], v[36:37]
	v_pk_mul_f32 v[8:9], v[8:9], v[24:25]
	v_pk_add_f32 v[10:11], v[28:29], 1.0 op_sel_hi:[1,0]
	v_mov_b32_e32 v32, v31
	v_pk_fma_f32 v[8:9], v[8:9], v[10:11], v[32:33]
	v_cvt_pk_bf16_f32 v8, v14, v8
	v_cvt_pk_bf16_f32 v9, v15, v9
	global_store_dwordx2 v[12:13], v[8:9], off offset:512
	v_lshl_add_u64 v[26:27], v[18:19], 0, v[56:57]
	v_lshl_add_u64 v[14:15], v[20:21], 0, v[56:57]
	global_load_dwordx4 v[8:11], v[48:49], off offset:2048
	global_load_dwordx4 v[22:25], v[14:15], off
	s_nop 0
	global_load_dwordx4 v[26:29], v[26:27], off
	v_mov_b32_e32 v14, v4
	v_mov_b32_e32 v15, v6
	v_pk_mul_f32 v[14:15], v[14:15], v[16:17] op_sel_hi:[1,0]
	v_mov_b32_e32 v6, v5
	v_pk_mul_f32 v[4:5], v[6:7], v[16:17] op_sel_hi:[1,0]
	s_waitcnt vmcnt(2)
	v_mov_b32_e32 v30, v8
	v_mov_b32_e32 v31, v10
	v_pk_mul_f32 v[14:15], v[14:15], v[30:31]
	s_waitcnt vmcnt(1)
	v_mov_b32_e32 v31, v24
	v_mov_b32_e32 v10, v9
	v_mov_b32_e32 v24, v23
	v_mov_b32_e32 v30, v22
	s_waitcnt vmcnt(0)
	v_mov_b32_e32 v33, v28
	v_pk_mul_f32 v[4:5], v[4:5], v[10:11]
	v_pk_add_f32 v[6:7], v[24:25], 1.0 op_sel_hi:[1,0]
	v_mov_b32_e32 v28, v27
	v_pk_add_f32 v[30:31], v[30:31], 1.0 op_sel_hi:[1,0]
	v_mov_b32_e32 v32, v26
	v_pk_fma_f32 v[4:5], v[4:5], v[6:7], v[28:29]
	v_pk_fma_f32 v[14:15], v[14:15], v[30:31], v[32:33]
	v_cvt_pk_bf16_f32 v5, v15, v5
	v_cvt_pk_bf16_f32 v4, v14, v4
	global_store_dwordx2 v[12:13], v[4:5], off offset:1024
	v_lshl_add_u64 v[8:9], v[20:21], 0, v[58:59]
	v_lshl_add_u64 v[14:15], v[18:19], 0, v[58:59]
	global_load_dwordx4 v[4:7], v[48:49], off offset:3072
	s_nop 0
	global_load_dwordx4 v[8:11], v[8:9], off
	s_nop 0
	global_load_dwordx4 v[18:21], v[14:15], off
	v_mov_b32_e32 v14, v0
	v_mov_b32_e32 v15, v2
	v_pk_mul_f32 v[14:15], v[14:15], v[16:17] op_sel_hi:[1,0]
	v_mov_b32_e32 v2, v1
	v_pk_mul_f32 v[0:1], v[2:3], v[16:17] op_sel_hi:[1,0]
	s_waitcnt vmcnt(2)
	v_mov_b32_e32 v22, v4
	v_mov_b32_e32 v23, v6
	v_pk_mul_f32 v[14:15], v[14:15], v[22:23]
	s_waitcnt vmcnt(1)
	v_mov_b32_e32 v23, v10
	v_mov_b32_e32 v6, v5
	v_mov_b32_e32 v10, v9
	v_mov_b32_e32 v22, v8
	s_waitcnt vmcnt(0)
	v_mov_b32_e32 v25, v20
	v_pk_mul_f32 v[0:1], v[0:1], v[6:7]
	v_pk_add_f32 v[2:3], v[10:11], 1.0 op_sel_hi:[1,0]
	v_mov_b32_e32 v20, v19
	v_pk_add_f32 v[22:23], v[22:23], 1.0 op_sel_hi:[1,0]
	v_mov_b32_e32 v24, v18
	v_pk_fma_f32 v[0:1], v[0:1], v[2:3], v[20:21]
	v_pk_fma_f32 v[14:15], v[14:15], v[22:23], v[24:25]
	v_cvt_pk_bf16_f32 v1, v15, v1
	v_cvt_pk_bf16_f32 v0, v14, v0
	global_store_dwordx2 v[12:13], v[0:1], off offset:1536
	s_andn2_b64 exec, exec, s[6:7]
	s_cbranch_execz .LBB0_188
